# GEMM K-loops: counter/pointer updates and loop test moved in front of the iteration's closing barrier (only the branch stays behind it)
# baseline (speedup 1.0000x reference)
; #define PG8_STAGE(bufoff, gbase, voff) do { _Pragma("unroll") for (int _i = 0; _i < 2; ++_i) \
;         __builtin_amdgcn_global_load_lds((const unsigned*)((const char*)(gbase) + (voff)[_i]), (PG8_LAS unsigned*)(lds + (bufoff) + ldsw + _i * 8192), 16, 0, 0); } while (0)
; #define PG8_LDA(dst, b, h) do { _Pragma("unroll") for (int m = 0; m < 4; ++m) _Pragma("unroll") for (int k = 0; k < 2; ++k) dst[m][k] = *(const PG8_LAS bf16x8*)(lds + PG8_SA(b, h) + aoff + m * 2048 + k * 1024); } while (0)
; #define PG8_LDB(dst, b, h) do { _Pragma("unroll") for (int n = 0; n < 2; ++n) _Pragma("unroll") for (int k = 0; k < 2; ++k) dst[n][k] = *(const PG8_LAS bf16x8*)(lds + PG8_SB(b, h) + boff + n * 2048 + k * 1024); } while (0)
; #define PG8_MMA(ai, bj, At, Bt) do { __builtin_amdgcn_s_setprio(1); _Pragma("unroll") for (int m = 0; m < 4; ++m) _Pragma("unroll") for (int n = 0; n < 2; ++n) _Pragma("unroll") for (int k = 0; k < 2; ++k) \
;         acc[ai][bj][m][n] = __builtin_amdgcn_mfma_f32_16x16x32_bf16(Bt[n][k], At[m][k], acc[ai][bj][m][n], 0, 0, 0); __builtin_amdgcn_s_setprio(0); } while (0)
; #define PG8_WAIT_V(n) asm volatile("s_waitcnt vmcnt(" #n ")" ::: "memory")
; #define PG8_BAR __builtin_amdgcn_s_barrier()
; template <class Epi, class Sched, bool ALIGN_EPI = false, bool SP2 = false>
; __device__ __forceinline__ void gemm_phase(PG8_LAS unsigned char* lds, const Gemm g, const Sched& S, const Epi& E) {
;     ...
;         for (int t = 0; t < nt; t += 2) {
;             const bool last = (t == nt - 2);
;             const char* a1 = cA + (size_t)(t + 1) * kstep;
;             const char* a2 = last ? nA : cA + (size_t)(t + 2) * kstep; const char* b2 = last ? nB : cB + (size_t)(t + 2) * kstep;
;             const char* a3 = a2 + kstep; const char* b3 = b2 + kstep;
;             if (last && has_next) S.a_ready(nxt);
;             if constexpr (SP2) {
;             PG8_LDB(B0, 0, 0); PG8_LDB(B1, 0, 1); PG8_SCHED; PG8_LDA(At, 0, 0); PG8_STAGE(PG8_SA(1, 1), a1 + hstep, voffA);
;             PG8_WAIT_V(8); PG8_WAIT_L(0); PG8_BAR; PG8_MMA(0, 0, At, B0); PG8_MMA(0, 1, At, B1); PG8_BAR; PG8_SCHED;
;             PG8_LDA(At, 0, 1); PG8_STAGE(PG8_SB(0, 0), b2, voffB); PG8_STAGE(PG8_SB(0, 1), b2 + hstep, voffB); PG8_STAGE(PG8_SA(0, 0), a2, voffA);
;             PG8_WAIT_V(8); PG8_WAIT_L(0); PG8_BAR; PG8_MMA(1, 0, At, B0); PG8_MMA(1, 1, At, B1); PG8_BAR; PG8_SCHED;
.LBB0_198:
	ds_read_b128 v[144:147], v153
	ds_read_b128 v[156:159], v153 offset:1024
	ds_read_b128 v[160:163], v153 offset:2048
	ds_read_b128 v[164:167], v153 offset:3072
	ds_read_b128 v[168:171], v154
	ds_read_b128 v[172:175], v154 offset:1024
	ds_read_b128 v[176:179], v154 offset:2048
	ds_read_b128 v[180:183], v154 offset:3072
	s_add_u32 s34, s30, 0xfffc0080
	s_addc_u32 s35, s31, -1
	s_cmp_eq_u32 s61, 12
	s_cselect_b32 s37, s23, s35
	s_cselect_b32 s36, s57, s34
	s_cselect_b32 s35, s13, s60
	s_cselect_b32 s34, s58, s59
	v_lshl_add_u64 v[218:219], s[30:31], 0, v[136:137]
	s_add_i32 m0, s29, 0xc000
	ds_read_b128 v[184:187], v155
	ds_read_b128 v[188:191], v155 offset:1024
	ds_read_b128 v[192:195], v155 offset:2048
	ds_read_b128 v[196:199], v155 offset:3072
	ds_read_b128 v[200:203], v155 offset:4096
	ds_read_b128 v[204:207], v155 offset:5120
	ds_read_b128 v[210:213], v155 offset:6144
	ds_read_b128 v[214:217], v155 offset:7168
	global_load_lds_dwordx4 v[218:219], off
	v_lshl_add_u64 v[218:219], s[30:31], 0, v[138:139]
	s_add_i32 m0, s29, 0xe000
	s_nop 0
	global_load_lds_dwordx4 v[218:219], off
	s_waitcnt vmcnt(8)
	s_waitcnt lgkmcnt(0)
	s_barrier
	s_setprio 1
	s_waitcnt lgkmcnt(0)
	v_mfma_f32_16x16x32_bf16 v[124:127], v[144:147], v[184:187], v[124:127]
	v_mfma_f32_16x16x32_bf16 v[116:119], v[160:163], v[184:187], v[116:119]
	v_mfma_f32_16x16x32_bf16 v[108:111], v[144:147], v[192:195], v[108:111]
	v_mfma_f32_16x16x32_bf16 v[100:103], v[160:163], v[192:195], v[100:103]
	v_mfma_f32_16x16x32_bf16 v[92:95], v[144:147], v[200:203], v[92:95]
	v_mfma_f32_16x16x32_bf16 v[84:87], v[160:163], v[200:203], v[84:87]
	v_mfma_f32_16x16x32_bf16 v[76:79], v[144:147], v[210:213], v[76:79]
	v_mfma_f32_16x16x32_bf16 v[68:71], v[160:163], v[210:213], v[68:71]
	v_mfma_f32_16x16x32_bf16 v[124:127], v[156:159], v[188:191], v[124:127]
	v_mfma_f32_16x16x32_bf16 v[116:119], v[164:167], v[188:191], v[116:119]
	v_mfma_f32_16x16x32_bf16 v[108:111], v[156:159], v[196:199], v[108:111]
	v_mfma_f32_16x16x32_bf16 v[100:103], v[164:167], v[196:199], v[100:103]
	v_mfma_f32_16x16x32_bf16 v[92:95], v[156:159], v[204:207], v[92:95]
	v_mfma_f32_16x16x32_bf16 v[84:87], v[164:167], v[204:207], v[84:87]
	v_mfma_f32_16x16x32_bf16 v[76:79], v[156:159], v[214:217], v[76:79]
	v_mfma_f32_16x16x32_bf16 v[68:71], v[164:167], v[214:217], v[68:71]
	s_setprio 0
	s_setprio 1
	v_mfma_f32_16x16x32_bf16 v[120:123], v[168:171], v[184:187], v[120:123]
	v_mfma_f32_16x16x32_bf16 v[112:115], v[176:179], v[184:187], v[112:115]
	v_mfma_f32_16x16x32_bf16 v[104:107], v[168:171], v[192:195], v[104:107]
	v_mfma_f32_16x16x32_bf16 v[96:99], v[176:179], v[192:195], v[96:99]
	v_mfma_f32_16x16x32_bf16 v[88:91], v[168:171], v[200:203], v[88:91]
	v_mfma_f32_16x16x32_bf16 v[80:83], v[176:179], v[200:203], v[80:83]
	v_mfma_f32_16x16x32_bf16 v[72:75], v[168:171], v[210:213], v[72:75]
	v_mfma_f32_16x16x32_bf16 v[64:67], v[176:179], v[210:213], v[64:67]
	v_mfma_f32_16x16x32_bf16 v[120:123], v[172:175], v[188:191], v[120:123]
	v_mfma_f32_16x16x32_bf16 v[112:115], v[180:183], v[188:191], v[112:115]
	v_mfma_f32_16x16x32_bf16 v[104:107], v[172:175], v[196:199], v[104:107]
	v_mfma_f32_16x16x32_bf16 v[96:99], v[180:183], v[196:199], v[96:99]
	v_mfma_f32_16x16x32_bf16 v[88:91], v[172:175], v[204:207], v[88:91]
	v_mfma_f32_16x16x32_bf16 v[80:83], v[180:183], v[204:207], v[80:83]
	v_mfma_f32_16x16x32_bf16 v[72:75], v[172:175], v[214:217], v[72:75]
	v_mfma_f32_16x16x32_bf16 v[64:67], v[180:183], v[214:217], v[64:67]
	s_setprio 0
	s_barrier
	s_add_i32 s62, s51, s40
	v_lshl_add_u64 v[218:219], s[34:35], 0, v[130:131]
	s_mov_b32 m0, s62
	ds_read_b128 v[184:187], v155 offset:16384
	ds_read_b128 v[188:191], v155 offset:17408
	ds_read_b128 v[192:195], v155 offset:18432
	ds_read_b128 v[196:199], v155 offset:19456
	ds_read_b128 v[200:203], v155 offset:20480
	ds_read_b128 v[204:207], v155 offset:21504
	ds_read_b128 v[210:213], v155 offset:22528
	ds_read_b128 v[214:217], v155 offset:23552
	global_load_lds_dwordx4 v[218:219], off
	s_add_i32 m0, s62, 0x2000
	s_add_u32 s62, s34, 0x40000
	v_lshl_add_u64 v[220:221], s[34:35], 0, v[134:135]
	s_addc_u32 s63, s35, 0
	s_add_i32 s64, s52, s40
	global_load_lds_dwordx4 v[220:221], off
	v_lshl_add_u64 v[222:223], s[62:63], 0, v[130:131]
	s_mov_b32 m0, s64
	v_lshl_add_u64 v[224:225], s[36:37], 0, v[132:133]
	global_load_lds_dwordx4 v[222:223], off
	v_lshl_add_u64 v[222:223], s[62:63], 0, v[134:135]
	s_add_i32 m0, s64, 0x2000
	s_nop 0
	global_load_lds_dwordx4 v[222:223], off
	v_lshl_add_u64 v[222:223], s[36:37], 0, v[128:129]
	s_mov_b32 m0, s29
	s_nop 0
	global_load_lds_dwordx4 v[222:223], off
	s_mov_b32 m0, s43
	s_nop 0
	global_load_lds_dwordx4 v[224:225], off
	s_waitcnt vmcnt(8)
	s_waitcnt lgkmcnt(0)
	s_barrier
; #define PG8_STAGE(bufoff, gbase, voff) do { _Pragma("unroll") for (int _i = 0; _i < 2; ++_i) \
;         __builtin_amdgcn_global_load_lds((const unsigned*)((const char*)(gbase) + (voff)[_i]), (PG8_LAS unsigned*)(lds + (bufoff) + ldsw + _i * 8192), 16, 0, 0); } while (0)
; #define PG8_LDA(dst, b, h) do { _Pragma("unroll") for (int m = 0; m < 4; ++m) _Pragma("unroll") for (int k = 0; k < 2; ++k) dst[m][k] = *(const PG8_LAS bf16x8*)(lds + PG8_SA(b, h) + aoff + m * 2048 + k * 1024); } while (0)
; #define PG8_LDB(dst, b, h) do { _Pragma("unroll") for (int n = 0; n < 2; ++n) _Pragma("unroll") for (int k = 0; k < 2; ++k) dst[n][k] = *(const PG8_LAS bf16x8*)(lds + PG8_SB(b, h) + boff + n * 2048 + k * 1024); } while (0)
; #define PG8_MMA(ai, bj, At, Bt) do { __builtin_amdgcn_s_setprio(1); _Pragma("unroll") for (int m = 0; m < 4; ++m) _Pragma("unroll") for (int n = 0; n < 2; ++n) _Pragma("unroll") for (int k = 0; k < 2; ++k) \
;         acc[ai][bj][m][n] = __builtin_amdgcn_mfma_f32_16x16x32_bf16(Bt[n][k], At[m][k], acc[ai][bj][m][n], 0, 0, 0); __builtin_amdgcn_s_setprio(0); } while (0)
; #define PG8_WAIT_V(n) asm volatile("s_waitcnt vmcnt(" #n ")" ::: "memory")
; #define PG8_WAIT_L(n) asm volatile("s_waitcnt lgkmcnt(" #n ")" ::: "memory")
; #define PG8_BAR __builtin_amdgcn_s_barrier()
; #define PG8_SCHED __builtin_amdgcn_sched_barrier(0)
; template <class Epi, class Sched, bool ALIGN_EPI = false, bool SP2 = false>
; __device__ __forceinline__ void gemm_phase(PG8_LAS unsigned char* lds, const Gemm g, const Sched& S, const Epi& E) {
;     ...
;             PG8_WAIT_V(8); PG8_WAIT_L(0); PG8_BAR; PG8_MMA(1, 0, At, B0); PG8_MMA(1, 1, At, B1); PG8_BAR; PG8_SCHED;
;             PG8_LDB(B0, 1, 0); PG8_LDB(B1, 1, 1); PG8_SCHED; PG8_LDA(At, 1, 0); PG8_STAGE(PG8_SA(0, 1), a2 + hstep, voffA);
;             PG8_WAIT_V(8); PG8_WAIT_L(0); PG8_BAR; PG8_MMA(0, 0, At, B0); PG8_MMA(0, 1, At, B1); PG8_BAR; PG8_SCHED;
	s_setprio 1
	s_waitcnt lgkmcnt(0)
	v_mfma_f32_16x16x32_bf16 v[60:63], v[144:147], v[184:187], v[60:63]
	v_mfma_f32_16x16x32_bf16 v[52:55], v[160:163], v[184:187], v[52:55]
	v_mfma_f32_16x16x32_bf16 v[44:47], v[144:147], v[192:195], v[44:47]
	v_mfma_f32_16x16x32_bf16 v[36:39], v[160:163], v[192:195], v[36:39]
	v_mfma_f32_16x16x32_bf16 v[28:31], v[144:147], v[200:203], v[28:31]
	v_mfma_f32_16x16x32_bf16 v[20:23], v[160:163], v[200:203], v[20:23]
	v_mfma_f32_16x16x32_bf16 v[12:15], v[144:147], v[210:213], v[12:15]
	v_mfma_f32_16x16x32_bf16 v[4:7], v[160:163], v[210:213], v[4:7]
	v_mfma_f32_16x16x32_bf16 v[60:63], v[156:159], v[188:191], v[60:63]
	v_mfma_f32_16x16x32_bf16 v[52:55], v[164:167], v[188:191], v[52:55]
	v_mfma_f32_16x16x32_bf16 v[44:47], v[156:159], v[196:199], v[44:47]
	v_mfma_f32_16x16x32_bf16 v[36:39], v[164:167], v[196:199], v[36:39]
	v_mfma_f32_16x16x32_bf16 v[28:31], v[156:159], v[204:207], v[28:31]
	v_mfma_f32_16x16x32_bf16 v[20:23], v[164:167], v[204:207], v[20:23]
	v_mfma_f32_16x16x32_bf16 v[12:15], v[156:159], v[214:217], v[12:15]
	v_mfma_f32_16x16x32_bf16 v[4:7], v[164:167], v[214:217], v[4:7]
	s_setprio 0
	s_setprio 1
	v_mfma_f32_16x16x32_bf16 v[56:59], v[168:171], v[184:187], v[56:59]
	v_mfma_f32_16x16x32_bf16 v[48:51], v[176:179], v[184:187], v[48:51]
	v_mfma_f32_16x16x32_bf16 v[40:43], v[168:171], v[192:195], v[40:43]
	v_mfma_f32_16x16x32_bf16 v[32:35], v[176:179], v[192:195], v[32:35]
	v_mfma_f32_16x16x32_bf16 v[24:27], v[168:171], v[200:203], v[24:27]
	v_mfma_f32_16x16x32_bf16 v[16:19], v[176:179], v[200:203], v[16:19]
	v_mfma_f32_16x16x32_bf16 v[8:11], v[168:171], v[210:213], v[8:11]
	v_mfma_f32_16x16x32_bf16 v[0:3], v[176:179], v[210:213], v[0:3]
	v_mfma_f32_16x16x32_bf16 v[56:59], v[172:175], v[188:191], v[56:59]
	v_mfma_f32_16x16x32_bf16 v[48:51], v[180:183], v[188:191], v[48:51]
	v_mfma_f32_16x16x32_bf16 v[40:43], v[172:175], v[196:199], v[40:43]
	v_mfma_f32_16x16x32_bf16 v[32:35], v[180:183], v[196:199], v[32:35]
	v_mfma_f32_16x16x32_bf16 v[24:27], v[172:175], v[204:207], v[24:27]
	v_mfma_f32_16x16x32_bf16 v[16:19], v[180:183], v[204:207], v[16:19]
	v_mfma_f32_16x16x32_bf16 v[8:11], v[172:175], v[214:217], v[8:11]
	v_mfma_f32_16x16x32_bf16 v[0:3], v[180:183], v[214:217], v[0:3]
	s_setprio 0
	s_barrier
	s_add_i32 s62, 0, 0x18000
	s_add_i32 s63, 0, 0x1c000
	v_add_u32_e32 v164, s62, v151
	v_add_u32_e32 v180, s63, v151
	ds_read_b128 v[144:147], v164
	ds_read_b128 v[156:159], v164 offset:1024
	ds_read_b128 v[160:163], v164 offset:2048
	ds_read_b128 v[164:167], v164 offset:3072
	ds_read_b128 v[168:171], v180
	ds_read_b128 v[172:175], v180 offset:1024
	ds_read_b128 v[176:179], v180 offset:2048
	ds_read_b128 v[180:183], v180 offset:3072
	s_add_u32 s36, s36, 0x40000
	s_addc_u32 s37, s37, 0
	s_mov_b32 m0, s44
	v_lshl_add_u64 v[226:227], s[36:37], 0, v[128:129]
	ds_read_b128 v[184:187], v155 offset:32768
	ds_read_b128 v[188:191], v155 offset:33792
	ds_read_b128 v[192:195], v155 offset:34816
	ds_read_b128 v[196:199], v155 offset:35840
	ds_read_b128 v[200:203], v155 offset:36864
	ds_read_b128 v[204:207], v155 offset:37888
	ds_read_b128 v[210:213], v155 offset:38912
	ds_read_b128 v[214:217], v155 offset:39936
	global_load_lds_dwordx4 v[226:227], off
	v_lshl_add_u64 v[226:227], s[36:37], 0, v[132:133]
	s_mov_b32 m0, s45
	s_nop 0
	global_load_lds_dwordx4 v[226:227], off
	s_waitcnt vmcnt(8)
	s_waitcnt lgkmcnt(0)
	s_barrier
	s_setprio 1
	s_waitcnt lgkmcnt(0)
	v_mfma_f32_16x16x32_bf16 v[124:127], v[144:147], v[184:187], v[124:127]
	v_mfma_f32_16x16x32_bf16 v[116:119], v[160:163], v[184:187], v[116:119]
	v_mfma_f32_16x16x32_bf16 v[108:111], v[144:147], v[192:195], v[108:111]
	v_mfma_f32_16x16x32_bf16 v[100:103], v[160:163], v[192:195], v[100:103]
	v_mfma_f32_16x16x32_bf16 v[92:95], v[144:147], v[200:203], v[92:95]
	v_mfma_f32_16x16x32_bf16 v[84:87], v[160:163], v[200:203], v[84:87]
	v_mfma_f32_16x16x32_bf16 v[76:79], v[144:147], v[210:213], v[76:79]
	v_mfma_f32_16x16x32_bf16 v[68:71], v[160:163], v[210:213], v[68:71]
	v_mfma_f32_16x16x32_bf16 v[124:127], v[156:159], v[188:191], v[124:127]
	v_mfma_f32_16x16x32_bf16 v[116:119], v[164:167], v[188:191], v[116:119]
	v_mfma_f32_16x16x32_bf16 v[108:111], v[156:159], v[196:199], v[108:111]
	v_mfma_f32_16x16x32_bf16 v[100:103], v[164:167], v[196:199], v[100:103]
	v_mfma_f32_16x16x32_bf16 v[92:95], v[156:159], v[204:207], v[92:95]
	v_mfma_f32_16x16x32_bf16 v[84:87], v[164:167], v[204:207], v[84:87]
	v_mfma_f32_16x16x32_bf16 v[76:79], v[156:159], v[214:217], v[76:79]
	v_mfma_f32_16x16x32_bf16 v[68:71], v[164:167], v[214:217], v[68:71]
	s_setprio 0
	s_setprio 1
	v_mfma_f32_16x16x32_bf16 v[120:123], v[168:171], v[184:187], v[120:123]
	v_mfma_f32_16x16x32_bf16 v[112:115], v[176:179], v[184:187], v[112:115]
	v_mfma_f32_16x16x32_bf16 v[104:107], v[168:171], v[192:195], v[104:107]
	v_mfma_f32_16x16x32_bf16 v[96:99], v[176:179], v[192:195], v[96:99]
	v_mfma_f32_16x16x32_bf16 v[88:91], v[168:171], v[200:203], v[88:91]
	v_mfma_f32_16x16x32_bf16 v[80:83], v[176:179], v[200:203], v[80:83]
	v_mfma_f32_16x16x32_bf16 v[72:75], v[168:171], v[210:213], v[72:75]
	v_mfma_f32_16x16x32_bf16 v[64:67], v[176:179], v[210:213], v[64:67]
	v_mfma_f32_16x16x32_bf16 v[120:123], v[172:175], v[188:191], v[120:123]
	v_mfma_f32_16x16x32_bf16 v[112:115], v[180:183], v[188:191], v[112:115]
	v_mfma_f32_16x16x32_bf16 v[104:107], v[172:175], v[196:199], v[104:107]
	v_mfma_f32_16x16x32_bf16 v[96:99], v[180:183], v[196:199], v[96:99]
	v_mfma_f32_16x16x32_bf16 v[88:91], v[172:175], v[204:207], v[88:91]
	v_mfma_f32_16x16x32_bf16 v[80:83], v[180:183], v[204:207], v[80:83]
	v_mfma_f32_16x16x32_bf16 v[72:75], v[172:175], v[214:217], v[72:75]
	v_mfma_f32_16x16x32_bf16 v[64:67], v[180:183], v[214:217], v[64:67]
	s_setprio 0
	s_barrier
; #define PG8_STAGE(bufoff, gbase, voff) do { _Pragma("unroll") for (int _i = 0; _i < 2; ++_i) \
;         __builtin_amdgcn_global_load_lds((const unsigned*)((const char*)(gbase) + (voff)[_i]), (PG8_LAS unsigned*)(lds + (bufoff) + ldsw + _i * 8192), 16, 0, 0); } while (0)
; #define PG8_LDA(dst, b, h) do { _Pragma("unroll") for (int m = 0; m < 4; ++m) _Pragma("unroll") for (int k = 0; k < 2; ++k) dst[m][k] = *(const PG8_LAS bf16x8*)(lds + PG8_SA(b, h) + aoff + m * 2048 + k * 1024); } while (0)
; #define PG8_MMA(ai, bj, At, Bt) do { __builtin_amdgcn_s_setprio(1); _Pragma("unroll") for (int m = 0; m < 4; ++m) _Pragma("unroll") for (int n = 0; n < 2; ++n) _Pragma("unroll") for (int k = 0; k < 2; ++k) \
;         acc[ai][bj][m][n] = __builtin_amdgcn_mfma_f32_16x16x32_bf16(Bt[n][k], At[m][k], acc[ai][bj][m][n], 0, 0, 0); __builtin_amdgcn_s_setprio(0); } while (0)
; #define PG8_WAIT_V(n) asm volatile("s_waitcnt vmcnt(" #n ")" ::: "memory")
; #define PG8_WAIT_L(n) asm volatile("s_waitcnt lgkmcnt(" #n ")" ::: "memory")
; #define PG8_BAR __builtin_amdgcn_s_barrier()
; #define PG8_SCHED __builtin_amdgcn_sched_barrier(0)
; template <class Epi, class Sched, bool ALIGN_EPI = false, bool SP2 = false>
; __device__ __forceinline__ void gemm_phase(PG8_LAS unsigned char* lds, const Gemm g, const Sched& S, const Epi& E) {
;     ...
;             PG8_LDA(At, 1, 1); PG8_STAGE(PG8_SB(1, 0), b3, voffB); PG8_STAGE(PG8_SB(1, 1), b3 + hstep, voffB); PG8_STAGE(PG8_SA(1, 0), a3, voffA);
;             PG8_WAIT_V(8); PG8_WAIT_L(0); PG8_BAR; PG8_MMA(1, 0, At, B0); PG8_MMA(1, 1, At, B1); PG8_BAR; PG8_SCHED;
;     ...
;         }
;         if constexpr (ALIGN_EPI) { if (wr == 0) PG8_BAR; }
	s_add_i32 s36, s62, s40
	v_lshl_add_u64 v[218:219], v[218:219], 0, s[8:9]
	s_mov_b32 m0, s36
	ds_read_b128 v[184:187], v155 offset:49152
	ds_read_b128 v[188:191], v155 offset:50176
	ds_read_b128 v[192:195], v155 offset:51200
	ds_read_b128 v[196:199], v155 offset:52224
	ds_read_b128 v[200:203], v155 offset:53248
	ds_read_b128 v[204:207], v155 offset:54272
	ds_read_b128 v[210:213], v155 offset:55296
	ds_read_b128 v[214:217], v155 offset:56320
	global_load_lds_dwordx4 v[218:219], off
	s_add_i32 m0, s36, 0x2000
	s_add_u32 s34, s34, 0x40080
	v_lshl_add_u64 v[218:219], v[220:221], 0, s[8:9]
	s_addc_u32 s35, s35, 0
	s_add_i32 s36, s63, s40
	global_load_lds_dwordx4 v[218:219], off
	v_lshl_add_u64 v[218:219], s[34:35], 0, v[130:131]
	s_mov_b32 m0, s36
	s_nop 0
	global_load_lds_dwordx4 v[218:219], off
	v_lshl_add_u64 v[218:219], s[34:35], 0, v[134:135]
	s_add_i32 m0, s36, 0x2000
	s_nop 0
	global_load_lds_dwordx4 v[218:219], off
	v_lshl_add_u64 v[218:219], v[222:223], 0, s[8:9]
	s_mov_b32 m0, s48
	s_nop 0
	global_load_lds_dwordx4 v[218:219], off
	v_lshl_add_u64 v[218:219], v[224:225], 0, s[8:9]
	s_mov_b32 m0, s49
	s_nop 0
	global_load_lds_dwordx4 v[218:219], off
	s_waitcnt vmcnt(8)
	s_waitcnt lgkmcnt(0)
	s_barrier
	s_setprio 1
	s_waitcnt lgkmcnt(0)
	v_mfma_f32_16x16x32_bf16 v[60:63], v[144:147], v[184:187], v[60:63]
	v_mfma_f32_16x16x32_bf16 v[52:55], v[160:163], v[184:187], v[52:55]
	v_mfma_f32_16x16x32_bf16 v[44:47], v[144:147], v[192:195], v[44:47]
	v_mfma_f32_16x16x32_bf16 v[36:39], v[160:163], v[192:195], v[36:39]
	v_mfma_f32_16x16x32_bf16 v[28:31], v[144:147], v[200:203], v[28:31]
	v_mfma_f32_16x16x32_bf16 v[20:23], v[160:163], v[200:203], v[20:23]
	v_mfma_f32_16x16x32_bf16 v[12:15], v[144:147], v[210:213], v[12:15]
	v_mfma_f32_16x16x32_bf16 v[4:7], v[160:163], v[210:213], v[4:7]
	v_mfma_f32_16x16x32_bf16 v[60:63], v[156:159], v[188:191], v[60:63]
	v_mfma_f32_16x16x32_bf16 v[52:55], v[164:167], v[188:191], v[52:55]
	v_mfma_f32_16x16x32_bf16 v[44:47], v[156:159], v[196:199], v[44:47]
	v_mfma_f32_16x16x32_bf16 v[36:39], v[164:167], v[196:199], v[36:39]
	v_mfma_f32_16x16x32_bf16 v[28:31], v[156:159], v[204:207], v[28:31]
	v_mfma_f32_16x16x32_bf16 v[20:23], v[164:167], v[204:207], v[20:23]
	v_mfma_f32_16x16x32_bf16 v[12:15], v[156:159], v[214:217], v[12:15]
	v_mfma_f32_16x16x32_bf16 v[4:7], v[164:167], v[214:217], v[4:7]
	s_setprio 0
	s_setprio 1
	v_mfma_f32_16x16x32_bf16 v[56:59], v[168:171], v[184:187], v[56:59]
	v_mfma_f32_16x16x32_bf16 v[48:51], v[176:179], v[184:187], v[48:51]
	v_mfma_f32_16x16x32_bf16 v[40:43], v[168:171], v[192:195], v[40:43]
	v_mfma_f32_16x16x32_bf16 v[32:35], v[176:179], v[192:195], v[32:35]
	v_mfma_f32_16x16x32_bf16 v[24:27], v[168:171], v[200:203], v[24:27]
	v_mfma_f32_16x16x32_bf16 v[16:19], v[176:179], v[200:203], v[16:19]
	v_mfma_f32_16x16x32_bf16 v[8:11], v[168:171], v[210:213], v[8:11]
	v_mfma_f32_16x16x32_bf16 v[0:3], v[176:179], v[210:213], v[0:3]
	v_mfma_f32_16x16x32_bf16 v[56:59], v[172:175], v[188:191], v[56:59]
	v_mfma_f32_16x16x32_bf16 v[48:51], v[180:183], v[188:191], v[48:51]
	v_mfma_f32_16x16x32_bf16 v[40:43], v[172:175], v[196:199], v[40:43]
	v_mfma_f32_16x16x32_bf16 v[32:35], v[180:183], v[196:199], v[32:35]
	v_mfma_f32_16x16x32_bf16 v[24:27], v[172:175], v[204:207], v[24:27]
	v_mfma_f32_16x16x32_bf16 v[16:19], v[180:183], v[204:207], v[16:19]
	v_mfma_f32_16x16x32_bf16 v[8:11], v[172:175], v[214:217], v[8:11]
	v_mfma_f32_16x16x32_bf16 v[0:3], v[180:183], v[214:217], v[0:3]
	s_setprio 0
	s_add_i32 s61, s61, 2
	s_add_u32 s30, s30, 0x100
	s_addc_u32 s31, s31, 0
	s_add_u32 s59, s59, 0x100
	s_addc_u32 s60, s60, 0
	s_cmp_gt_u32 s61, 13
	s_barrier
	s_cbranch_scc0 .LBB0_198
	s_and_b64 vcc, exec, s[10:11]
	s_cbranch_vccz .LBB0_201
	s_barrier

; #define PG8_STAGE(bufoff, gbase, voff) do { _Pragma("unroll") for (int _i = 0; _i < 2; ++_i) \
;         __builtin_amdgcn_global_load_lds((const unsigned*)((const char*)(gbase) + (voff)[_i]), (PG8_LAS unsigned*)(lds + (bufoff) + ldsw + _i * 8192), 16, 0, 0); } while (0)
; #define PG8_LDA(dst, b, h) do { _Pragma("unroll") for (int m = 0; m < 4; ++m) _Pragma("unroll") for (int k = 0; k < 2; ++k) dst[m][k] = *(const PG8_LAS bf16x8*)(lds + PG8_SA(b, h) + aoff + m * 2048 + k * 1024); } while (0)
; #define PG8_LDB(dst, b, h) do { _Pragma("unroll") for (int n = 0; n < 2; ++n) _Pragma("unroll") for (int k = 0; k < 2; ++k) dst[n][k] = *(const PG8_LAS bf16x8*)(lds + PG8_SB(b, h) + boff + n * 2048 + k * 1024); } while (0)
; #define PG8_MMA(ai, bj, At, Bt) do { __builtin_amdgcn_s_setprio(1); _Pragma("unroll") for (int m = 0; m < 4; ++m) _Pragma("unroll") for (int n = 0; n < 2; ++n) _Pragma("unroll") for (int k = 0; k < 2; ++k) \
;         acc[ai][bj][m][n] = __builtin_amdgcn_mfma_f32_16x16x32_bf16(Bt[n][k], At[m][k], acc[ai][bj][m][n], 0, 0, 0); __builtin_amdgcn_s_setprio(0); } while (0)
; #define PG8_WAIT_V(n) asm volatile("s_waitcnt vmcnt(" #n ")" ::: "memory")
; #define PG8_WAIT_L(n) asm volatile("s_waitcnt lgkmcnt(" #n ")" ::: "memory")
; #define PG8_BAR __builtin_amdgcn_s_barrier()
; #define PG8_SCHED __builtin_amdgcn_sched_barrier(0)
; template <class Epi, class Sched, bool ALIGN_EPI = false, bool SP2 = false>
; __device__ __forceinline__ void gemm_phase(PG8_LAS unsigned char* lds, const Gemm g, const Sched& S, const Epi& E) {
;     ...
;         for (int t = 0; t < nt; t += 2) {
;             const bool last = (t == nt - 2);
;             const char* a1 = cA + (size_t)(t + 1) * kstep;
;             const char* a2 = last ? nA : cA + (size_t)(t + 2) * kstep; const char* b2 = last ? nB : cB + (size_t)(t + 2) * kstep;
;             const char* a3 = a2 + kstep; const char* b3 = b2 + kstep;
;             if (last && has_next) S.a_ready(nxt);
;             if constexpr (SP2) {
;             PG8_LDB(B0, 0, 0); PG8_LDB(B1, 0, 1); PG8_SCHED; PG8_LDA(At, 0, 0); PG8_STAGE(PG8_SA(1, 1), a1 + hstep, voffA);
;             PG8_WAIT_V(8); PG8_WAIT_L(0); PG8_BAR; PG8_MMA(0, 0, At, B0); PG8_MMA(0, 1, At, B1); PG8_BAR; PG8_SCHED;
.LBB0_314:
	ds_read_b128 v[144:147], v152
	ds_read_b128 v[156:159], v152 offset:1024
	ds_read_b128 v[160:163], v152 offset:2048
	ds_read_b128 v[164:167], v152 offset:3072
	ds_read_b128 v[168:171], v153
	ds_read_b128 v[172:175], v153 offset:1024
	ds_read_b128 v[176:179], v153 offset:2048
	ds_read_b128 v[180:183], v153 offset:3072
	s_add_u32 s26, s24, 0xfff50080
	s_addc_u32 s27, s25, -1
	s_cmp_eq_u32 s57, 40
	s_cselect_b32 s29, s1, s27
	s_cselect_b32 s28, s0, s26
	s_cselect_b32 s27, s23, s56
	s_cselect_b32 s26, s22, s53
	v_lshl_add_u64 v[218:219], s[24:25], 0, v[136:137]
	s_add_i32 m0, s37, 0xc000
	ds_read_b128 v[184:187], v154
	ds_read_b128 v[188:191], v154 offset:1024
	ds_read_b128 v[192:195], v154 offset:2048
	ds_read_b128 v[196:199], v154 offset:3072
	ds_read_b128 v[200:203], v154 offset:4096
	ds_read_b128 v[204:207], v154 offset:5120
	ds_read_b128 v[210:213], v154 offset:6144
	ds_read_b128 v[214:217], v154 offset:7168
	global_load_lds_dwordx4 v[218:219], off
	v_lshl_add_u64 v[218:219], s[24:25], 0, v[138:139]
	s_add_i32 m0, s37, 0xe000
	s_nop 0
	global_load_lds_dwordx4 v[218:219], off
	s_waitcnt vmcnt(8)
	s_waitcnt lgkmcnt(0)
	s_barrier
	s_setprio 1
	s_waitcnt lgkmcnt(0)
	v_mfma_f32_16x16x32_bf16 v[124:127], v[144:147], v[184:187], v[124:127]
	v_mfma_f32_16x16x32_bf16 v[120:123], v[160:163], v[184:187], v[120:123]
	v_mfma_f32_16x16x32_bf16 v[108:111], v[144:147], v[192:195], v[108:111]
	v_mfma_f32_16x16x32_bf16 v[104:107], v[160:163], v[192:195], v[104:107]
	v_mfma_f32_16x16x32_bf16 v[92:95], v[144:147], v[200:203], v[92:95]
	v_mfma_f32_16x16x32_bf16 v[88:91], v[160:163], v[200:203], v[88:91]
	v_mfma_f32_16x16x32_bf16 v[76:79], v[144:147], v[210:213], v[76:79]
	v_mfma_f32_16x16x32_bf16 v[72:75], v[160:163], v[210:213], v[72:75]
	v_mfma_f32_16x16x32_bf16 v[124:127], v[156:159], v[188:191], v[124:127]
	v_mfma_f32_16x16x32_bf16 v[120:123], v[164:167], v[188:191], v[120:123]
	v_mfma_f32_16x16x32_bf16 v[108:111], v[156:159], v[196:199], v[108:111]
	v_mfma_f32_16x16x32_bf16 v[104:107], v[164:167], v[196:199], v[104:107]
	v_mfma_f32_16x16x32_bf16 v[92:95], v[156:159], v[204:207], v[92:95]
	v_mfma_f32_16x16x32_bf16 v[88:91], v[164:167], v[204:207], v[88:91]
	v_mfma_f32_16x16x32_bf16 v[76:79], v[156:159], v[214:217], v[76:79]
	v_mfma_f32_16x16x32_bf16 v[72:75], v[164:167], v[214:217], v[72:75]
	s_setprio 0
	s_setprio 1
	v_mfma_f32_16x16x32_bf16 v[116:119], v[168:171], v[184:187], v[116:119]
	v_mfma_f32_16x16x32_bf16 v[112:115], v[176:179], v[184:187], v[112:115]
	v_mfma_f32_16x16x32_bf16 v[100:103], v[168:171], v[192:195], v[100:103]
	v_mfma_f32_16x16x32_bf16 v[96:99], v[176:179], v[192:195], v[96:99]
	v_mfma_f32_16x16x32_bf16 v[84:87], v[168:171], v[200:203], v[84:87]
	v_mfma_f32_16x16x32_bf16 v[80:83], v[176:179], v[200:203], v[80:83]
	v_mfma_f32_16x16x32_bf16 v[68:71], v[168:171], v[210:213], v[68:71]
	v_mfma_f32_16x16x32_bf16 v[64:67], v[176:179], v[210:213], v[64:67]
	v_mfma_f32_16x16x32_bf16 v[116:119], v[172:175], v[188:191], v[116:119]
	v_mfma_f32_16x16x32_bf16 v[112:115], v[180:183], v[188:191], v[112:115]
	v_mfma_f32_16x16x32_bf16 v[100:103], v[172:175], v[196:199], v[100:103]
	v_mfma_f32_16x16x32_bf16 v[96:99], v[180:183], v[196:199], v[96:99]
	v_mfma_f32_16x16x32_bf16 v[84:87], v[172:175], v[204:207], v[84:87]
	v_mfma_f32_16x16x32_bf16 v[80:83], v[180:183], v[204:207], v[80:83]
	v_mfma_f32_16x16x32_bf16 v[68:71], v[172:175], v[214:217], v[68:71]
	v_mfma_f32_16x16x32_bf16 v[64:67], v[180:183], v[214:217], v[64:67]
	s_setprio 0
	s_barrier
	s_add_i32 s58, s47, s36
	v_lshl_add_u64 v[218:219], s[26:27], 0, v[130:131]
	s_mov_b32 m0, s58
	ds_read_b128 v[184:187], v154 offset:16384
	ds_read_b128 v[188:191], v154 offset:17408
	ds_read_b128 v[192:195], v154 offset:18432
	ds_read_b128 v[196:199], v154 offset:19456
	ds_read_b128 v[200:203], v154 offset:20480
	ds_read_b128 v[204:207], v154 offset:21504
	ds_read_b128 v[210:213], v154 offset:22528
	ds_read_b128 v[214:217], v154 offset:23552
	global_load_lds_dwordx4 v[218:219], off
	s_add_i32 m0, s58, 0x2000
	s_add_u32 s58, s26, 0xb0000
	v_lshl_add_u64 v[220:221], s[26:27], 0, v[134:135]
	s_addc_u32 s59, s27, 0
	s_add_i32 s60, s48, s36
	global_load_lds_dwordx4 v[220:221], off
	v_lshl_add_u64 v[222:223], s[58:59], 0, v[130:131]
	s_mov_b32 m0, s60
	v_lshl_add_u64 v[224:225], s[28:29], 0, v[132:133]
	global_load_lds_dwordx4 v[222:223], off
	v_lshl_add_u64 v[222:223], s[58:59], 0, v[134:135]
	s_add_i32 m0, s60, 0x2000
	s_nop 0
	global_load_lds_dwordx4 v[222:223], off
	v_lshl_add_u64 v[222:223], s[28:29], 0, v[128:129]
	s_mov_b32 m0, s37
	s_nop 0
	global_load_lds_dwordx4 v[222:223], off
	s_mov_b32 m0, s38
	s_nop 0
	global_load_lds_dwordx4 v[224:225], off
	s_waitcnt vmcnt(8)
	s_waitcnt lgkmcnt(0)
	s_barrier
; #define PG8_STAGE(bufoff, gbase, voff) do { _Pragma("unroll") for (int _i = 0; _i < 2; ++_i) \
;         __builtin_amdgcn_global_load_lds((const unsigned*)((const char*)(gbase) + (voff)[_i]), (PG8_LAS unsigned*)(lds + (bufoff) + ldsw + _i * 8192), 16, 0, 0); } while (0)
; #define PG8_LDA(dst, b, h) do { _Pragma("unroll") for (int m = 0; m < 4; ++m) _Pragma("unroll") for (int k = 0; k < 2; ++k) dst[m][k] = *(const PG8_LAS bf16x8*)(lds + PG8_SA(b, h) + aoff + m * 2048 + k * 1024); } while (0)
; #define PG8_LDB(dst, b, h) do { _Pragma("unroll") for (int n = 0; n < 2; ++n) _Pragma("unroll") for (int k = 0; k < 2; ++k) dst[n][k] = *(const PG8_LAS bf16x8*)(lds + PG8_SB(b, h) + boff + n * 2048 + k * 1024); } while (0)
; #define PG8_MMA(ai, bj, At, Bt) do { __builtin_amdgcn_s_setprio(1); _Pragma("unroll") for (int m = 0; m < 4; ++m) _Pragma("unroll") for (int n = 0; n < 2; ++n) _Pragma("unroll") for (int k = 0; k < 2; ++k) \
;         acc[ai][bj][m][n] = __builtin_amdgcn_mfma_f32_16x16x32_bf16(Bt[n][k], At[m][k], acc[ai][bj][m][n], 0, 0, 0); __builtin_amdgcn_s_setprio(0); } while (0)
; #define PG8_WAIT_V(n) asm volatile("s_waitcnt vmcnt(" #n ")" ::: "memory")
; #define PG8_WAIT_L(n) asm volatile("s_waitcnt lgkmcnt(" #n ")" ::: "memory")
; #define PG8_BAR __builtin_amdgcn_s_barrier()
; #define PG8_SCHED __builtin_amdgcn_sched_barrier(0)
; template <class Epi, class Sched, bool ALIGN_EPI = false, bool SP2 = false>
; __device__ __forceinline__ void gemm_phase(PG8_LAS unsigned char* lds, const Gemm g, const Sched& S, const Epi& E) {
;     ...
;             PG8_WAIT_V(8); PG8_WAIT_L(0); PG8_BAR; PG8_MMA(1, 0, At, B0); PG8_MMA(1, 1, At, B1); PG8_BAR; PG8_SCHED;
;             PG8_LDB(B0, 1, 0); PG8_LDB(B1, 1, 1); PG8_SCHED; PG8_LDA(At, 1, 0); PG8_STAGE(PG8_SA(0, 1), a2 + hstep, voffA);
;             PG8_WAIT_V(8); PG8_WAIT_L(0); PG8_BAR; PG8_MMA(0, 0, At, B0); PG8_MMA(0, 1, At, B1); PG8_BAR; PG8_SCHED;
	s_setprio 1
	s_waitcnt lgkmcnt(0)
	v_mfma_f32_16x16x32_bf16 v[60:63], v[144:147], v[184:187], v[60:63]
	v_mfma_f32_16x16x32_bf16 v[56:59], v[160:163], v[184:187], v[56:59]
	v_mfma_f32_16x16x32_bf16 v[44:47], v[144:147], v[192:195], v[44:47]
	v_mfma_f32_16x16x32_bf16 v[40:43], v[160:163], v[192:195], v[40:43]
	v_mfma_f32_16x16x32_bf16 v[28:31], v[144:147], v[200:203], v[28:31]
	v_mfma_f32_16x16x32_bf16 v[24:27], v[160:163], v[200:203], v[24:27]
	v_mfma_f32_16x16x32_bf16 v[12:15], v[144:147], v[210:213], v[12:15]
	v_mfma_f32_16x16x32_bf16 v[8:11], v[160:163], v[210:213], v[8:11]
	v_mfma_f32_16x16x32_bf16 v[60:63], v[156:159], v[188:191], v[60:63]
	v_mfma_f32_16x16x32_bf16 v[56:59], v[164:167], v[188:191], v[56:59]
	v_mfma_f32_16x16x32_bf16 v[44:47], v[156:159], v[196:199], v[44:47]
	v_mfma_f32_16x16x32_bf16 v[40:43], v[164:167], v[196:199], v[40:43]
	v_mfma_f32_16x16x32_bf16 v[28:31], v[156:159], v[204:207], v[28:31]
	v_mfma_f32_16x16x32_bf16 v[24:27], v[164:167], v[204:207], v[24:27]
	v_mfma_f32_16x16x32_bf16 v[12:15], v[156:159], v[214:217], v[12:15]
	v_mfma_f32_16x16x32_bf16 v[8:11], v[164:167], v[214:217], v[8:11]
	s_setprio 0
	s_setprio 1
	v_mfma_f32_16x16x32_bf16 v[52:55], v[168:171], v[184:187], v[52:55]
	v_mfma_f32_16x16x32_bf16 v[48:51], v[176:179], v[184:187], v[48:51]
	v_mfma_f32_16x16x32_bf16 v[36:39], v[168:171], v[192:195], v[36:39]
	v_mfma_f32_16x16x32_bf16 v[32:35], v[176:179], v[192:195], v[32:35]
	v_mfma_f32_16x16x32_bf16 v[20:23], v[168:171], v[200:203], v[20:23]
	v_mfma_f32_16x16x32_bf16 v[16:19], v[176:179], v[200:203], v[16:19]
	v_mfma_f32_16x16x32_bf16 v[4:7], v[168:171], v[210:213], v[4:7]
	v_mfma_f32_16x16x32_bf16 v[0:3], v[176:179], v[210:213], v[0:3]
	v_mfma_f32_16x16x32_bf16 v[52:55], v[172:175], v[188:191], v[52:55]
	v_mfma_f32_16x16x32_bf16 v[48:51], v[180:183], v[188:191], v[48:51]
	v_mfma_f32_16x16x32_bf16 v[36:39], v[172:175], v[196:199], v[36:39]
	v_mfma_f32_16x16x32_bf16 v[32:35], v[180:183], v[196:199], v[32:35]
	v_mfma_f32_16x16x32_bf16 v[20:23], v[172:175], v[204:207], v[20:23]
	v_mfma_f32_16x16x32_bf16 v[16:19], v[180:183], v[204:207], v[16:19]
	v_mfma_f32_16x16x32_bf16 v[4:7], v[172:175], v[214:217], v[4:7]
	v_mfma_f32_16x16x32_bf16 v[0:3], v[180:183], v[214:217], v[0:3]
	s_setprio 0
	s_barrier
	s_add_i32 s58, 0, 0x18000
	s_add_i32 s59, 0, 0x1c000
	v_add_u32_e32 v164, s58, v150
	v_add_u32_e32 v180, s59, v150
	ds_read_b128 v[144:147], v164
	ds_read_b128 v[156:159], v164 offset:1024
	ds_read_b128 v[160:163], v164 offset:2048
	ds_read_b128 v[164:167], v164 offset:3072
	ds_read_b128 v[168:171], v180
	ds_read_b128 v[172:175], v180 offset:1024
	ds_read_b128 v[176:179], v180 offset:2048
	ds_read_b128 v[180:183], v180 offset:3072
	s_add_u32 s28, s28, 0xb0000
	s_addc_u32 s29, s29, 0
	s_mov_b32 m0, s39
	v_lshl_add_u64 v[226:227], s[28:29], 0, v[128:129]
	ds_read_b128 v[184:187], v154 offset:32768
	ds_read_b128 v[188:191], v154 offset:33792
	ds_read_b128 v[192:195], v154 offset:34816
	ds_read_b128 v[196:199], v154 offset:35840
	ds_read_b128 v[200:203], v154 offset:36864
	ds_read_b128 v[204:207], v154 offset:37888
	ds_read_b128 v[210:213], v154 offset:38912
	ds_read_b128 v[214:217], v154 offset:39936
	global_load_lds_dwordx4 v[226:227], off
	v_lshl_add_u64 v[226:227], s[28:29], 0, v[132:133]
	s_mov_b32 m0, s40
	s_nop 0
	global_load_lds_dwordx4 v[226:227], off
	s_waitcnt vmcnt(8)
	s_waitcnt lgkmcnt(0)
	s_barrier
	s_setprio 1
	s_waitcnt lgkmcnt(0)
	v_mfma_f32_16x16x32_bf16 v[124:127], v[144:147], v[184:187], v[124:127]
	v_mfma_f32_16x16x32_bf16 v[120:123], v[160:163], v[184:187], v[120:123]
	v_mfma_f32_16x16x32_bf16 v[108:111], v[144:147], v[192:195], v[108:111]
	v_mfma_f32_16x16x32_bf16 v[104:107], v[160:163], v[192:195], v[104:107]
	v_mfma_f32_16x16x32_bf16 v[92:95], v[144:147], v[200:203], v[92:95]
	v_mfma_f32_16x16x32_bf16 v[88:91], v[160:163], v[200:203], v[88:91]
	v_mfma_f32_16x16x32_bf16 v[76:79], v[144:147], v[210:213], v[76:79]
	v_mfma_f32_16x16x32_bf16 v[72:75], v[160:163], v[210:213], v[72:75]
	v_mfma_f32_16x16x32_bf16 v[124:127], v[156:159], v[188:191], v[124:127]
	v_mfma_f32_16x16x32_bf16 v[120:123], v[164:167], v[188:191], v[120:123]
	v_mfma_f32_16x16x32_bf16 v[108:111], v[156:159], v[196:199], v[108:111]
	v_mfma_f32_16x16x32_bf16 v[104:107], v[164:167], v[196:199], v[104:107]
	v_mfma_f32_16x16x32_bf16 v[92:95], v[156:159], v[204:207], v[92:95]
	v_mfma_f32_16x16x32_bf16 v[88:91], v[164:167], v[204:207], v[88:91]
	v_mfma_f32_16x16x32_bf16 v[76:79], v[156:159], v[214:217], v[76:79]
	v_mfma_f32_16x16x32_bf16 v[72:75], v[164:167], v[214:217], v[72:75]
	s_setprio 0
	s_setprio 1
	v_mfma_f32_16x16x32_bf16 v[116:119], v[168:171], v[184:187], v[116:119]
	v_mfma_f32_16x16x32_bf16 v[112:115], v[176:179], v[184:187], v[112:115]
	v_mfma_f32_16x16x32_bf16 v[100:103], v[168:171], v[192:195], v[100:103]
	v_mfma_f32_16x16x32_bf16 v[96:99], v[176:179], v[192:195], v[96:99]
	v_mfma_f32_16x16x32_bf16 v[84:87], v[168:171], v[200:203], v[84:87]
	v_mfma_f32_16x16x32_bf16 v[80:83], v[176:179], v[200:203], v[80:83]
	v_mfma_f32_16x16x32_bf16 v[68:71], v[168:171], v[210:213], v[68:71]
	v_mfma_f32_16x16x32_bf16 v[64:67], v[176:179], v[210:213], v[64:67]
	v_mfma_f32_16x16x32_bf16 v[116:119], v[172:175], v[188:191], v[116:119]
	v_mfma_f32_16x16x32_bf16 v[112:115], v[180:183], v[188:191], v[112:115]
	v_mfma_f32_16x16x32_bf16 v[100:103], v[172:175], v[196:199], v[100:103]
	v_mfma_f32_16x16x32_bf16 v[96:99], v[180:183], v[196:199], v[96:99]
	v_mfma_f32_16x16x32_bf16 v[84:87], v[172:175], v[204:207], v[84:87]
	v_mfma_f32_16x16x32_bf16 v[80:83], v[180:183], v[204:207], v[80:83]
	v_mfma_f32_16x16x32_bf16 v[68:71], v[172:175], v[214:217], v[68:71]
	v_mfma_f32_16x16x32_bf16 v[64:67], v[180:183], v[214:217], v[64:67]
	s_setprio 0
	s_barrier
; #define PG8_STAGE(bufoff, gbase, voff) do { _Pragma("unroll") for (int _i = 0; _i < 2; ++_i) \
;         __builtin_amdgcn_global_load_lds((const unsigned*)((const char*)(gbase) + (voff)[_i]), (PG8_LAS unsigned*)(lds + (bufoff) + ldsw + _i * 8192), 16, 0, 0); } while (0)
; #define PG8_LDA(dst, b, h) do { _Pragma("unroll") for (int m = 0; m < 4; ++m) _Pragma("unroll") for (int k = 0; k < 2; ++k) dst[m][k] = *(const PG8_LAS bf16x8*)(lds + PG8_SA(b, h) + aoff + m * 2048 + k * 1024); } while (0)
; #define PG8_MMA(ai, bj, At, Bt) do { __builtin_amdgcn_s_setprio(1); _Pragma("unroll") for (int m = 0; m < 4; ++m) _Pragma("unroll") for (int n = 0; n < 2; ++n) _Pragma("unroll") for (int k = 0; k < 2; ++k) \
;         acc[ai][bj][m][n] = __builtin_amdgcn_mfma_f32_16x16x32_bf16(Bt[n][k], At[m][k], acc[ai][bj][m][n], 0, 0, 0); __builtin_amdgcn_s_setprio(0); } while (0)
; #define PG8_WAIT_V(n) asm volatile("s_waitcnt vmcnt(" #n ")" ::: "memory")
; #define PG8_WAIT_L(n) asm volatile("s_waitcnt lgkmcnt(" #n ")" ::: "memory")
; #define PG8_BAR __builtin_amdgcn_s_barrier()
; #define PG8_SCHED __builtin_amdgcn_sched_barrier(0)
; template <class Epi, class Sched, bool ALIGN_EPI = false, bool SP2 = false>
; __device__ __forceinline__ void gemm_phase(PG8_LAS unsigned char* lds, const Gemm g, const Sched& S, const Epi& E) {
;     ...
;         for (int t = 0; t < nt; t += 2) {
;             const bool last = (t == nt - 2);
;             const char* a1 = cA + (size_t)(t + 1) * kstep;
;             const char* a2 = last ? nA : cA + (size_t)(t + 2) * kstep; const char* b2 = last ? nB : cB + (size_t)(t + 2) * kstep;
;             const char* a3 = a2 + kstep; const char* b3 = b2 + kstep;
;     ...
;             PG8_LDA(At, 1, 1); PG8_STAGE(PG8_SB(1, 0), b3, voffB); PG8_STAGE(PG8_SB(1, 1), b3 + hstep, voffB); PG8_STAGE(PG8_SA(1, 0), a3, voffA);
;             PG8_WAIT_V(8); PG8_WAIT_L(0); PG8_BAR; PG8_MMA(1, 0, At, B0); PG8_MMA(1, 1, At, B1); PG8_BAR; PG8_SCHED;
	s_add_i32 s28, s58, s36
	v_lshl_add_u64 v[218:219], v[218:219], 0, s[14:15]
	s_mov_b32 m0, s28
	ds_read_b128 v[184:187], v154 offset:49152
	ds_read_b128 v[188:191], v154 offset:50176
	ds_read_b128 v[192:195], v154 offset:51200
	ds_read_b128 v[196:199], v154 offset:52224
	ds_read_b128 v[200:203], v154 offset:53248
	ds_read_b128 v[204:207], v154 offset:54272
	ds_read_b128 v[210:213], v154 offset:55296
	ds_read_b128 v[214:217], v154 offset:56320
	global_load_lds_dwordx4 v[218:219], off
	s_add_i32 m0, s28, 0x2000
	s_add_u32 s26, s26, 0xb0080
	v_lshl_add_u64 v[218:219], v[220:221], 0, s[14:15]
	s_addc_u32 s27, s27, 0
	s_add_i32 s28, s59, s36
	global_load_lds_dwordx4 v[218:219], off
	v_lshl_add_u64 v[218:219], s[26:27], 0, v[130:131]
	s_mov_b32 m0, s28
	s_nop 0
	global_load_lds_dwordx4 v[218:219], off
	v_lshl_add_u64 v[218:219], s[26:27], 0, v[134:135]
	s_add_i32 m0, s28, 0x2000
	s_nop 0
	global_load_lds_dwordx4 v[218:219], off
	v_lshl_add_u64 v[218:219], v[222:223], 0, s[14:15]
	s_mov_b32 m0, s42
	s_nop 0
	global_load_lds_dwordx4 v[218:219], off
	v_lshl_add_u64 v[218:219], v[224:225], 0, s[14:15]
	s_mov_b32 m0, s43
	s_nop 0
	global_load_lds_dwordx4 v[218:219], off
	s_waitcnt vmcnt(8)
	s_waitcnt lgkmcnt(0)
	s_barrier
	s_setprio 1
	s_waitcnt lgkmcnt(0)
	v_mfma_f32_16x16x32_bf16 v[60:63], v[144:147], v[184:187], v[60:63]
	v_mfma_f32_16x16x32_bf16 v[56:59], v[160:163], v[184:187], v[56:59]
	v_mfma_f32_16x16x32_bf16 v[44:47], v[144:147], v[192:195], v[44:47]
	v_mfma_f32_16x16x32_bf16 v[40:43], v[160:163], v[192:195], v[40:43]
	v_mfma_f32_16x16x32_bf16 v[28:31], v[144:147], v[200:203], v[28:31]
	v_mfma_f32_16x16x32_bf16 v[24:27], v[160:163], v[200:203], v[24:27]
	v_mfma_f32_16x16x32_bf16 v[12:15], v[144:147], v[210:213], v[12:15]
	v_mfma_f32_16x16x32_bf16 v[8:11], v[160:163], v[210:213], v[8:11]
	v_mfma_f32_16x16x32_bf16 v[60:63], v[156:159], v[188:191], v[60:63]
	v_mfma_f32_16x16x32_bf16 v[56:59], v[164:167], v[188:191], v[56:59]
	v_mfma_f32_16x16x32_bf16 v[44:47], v[156:159], v[196:199], v[44:47]
	v_mfma_f32_16x16x32_bf16 v[40:43], v[164:167], v[196:199], v[40:43]
	v_mfma_f32_16x16x32_bf16 v[28:31], v[156:159], v[204:207], v[28:31]
	v_mfma_f32_16x16x32_bf16 v[24:27], v[164:167], v[204:207], v[24:27]
	v_mfma_f32_16x16x32_bf16 v[12:15], v[156:159], v[214:217], v[12:15]
	v_mfma_f32_16x16x32_bf16 v[8:11], v[164:167], v[214:217], v[8:11]
	s_setprio 0
	s_setprio 1
	v_mfma_f32_16x16x32_bf16 v[52:55], v[168:171], v[184:187], v[52:55]
	v_mfma_f32_16x16x32_bf16 v[48:51], v[176:179], v[184:187], v[48:51]
	v_mfma_f32_16x16x32_bf16 v[36:39], v[168:171], v[192:195], v[36:39]
	v_mfma_f32_16x16x32_bf16 v[32:35], v[176:179], v[192:195], v[32:35]
	v_mfma_f32_16x16x32_bf16 v[20:23], v[168:171], v[200:203], v[20:23]
	v_mfma_f32_16x16x32_bf16 v[16:19], v[176:179], v[200:203], v[16:19]
	v_mfma_f32_16x16x32_bf16 v[4:7], v[168:171], v[210:213], v[4:7]
	v_mfma_f32_16x16x32_bf16 v[0:3], v[176:179], v[210:213], v[0:3]
	v_mfma_f32_16x16x32_bf16 v[52:55], v[172:175], v[188:191], v[52:55]
	v_mfma_f32_16x16x32_bf16 v[48:51], v[180:183], v[188:191], v[48:51]
	v_mfma_f32_16x16x32_bf16 v[36:39], v[172:175], v[196:199], v[36:39]
	v_mfma_f32_16x16x32_bf16 v[32:35], v[180:183], v[196:199], v[32:35]
	v_mfma_f32_16x16x32_bf16 v[20:23], v[172:175], v[204:207], v[20:23]
	v_mfma_f32_16x16x32_bf16 v[16:19], v[180:183], v[204:207], v[16:19]
	v_mfma_f32_16x16x32_bf16 v[4:7], v[172:175], v[214:217], v[4:7]
	v_mfma_f32_16x16x32_bf16 v[0:3], v[180:183], v[214:217], v[0:3]
	s_setprio 0
	s_add_i32 s57, s57, 2
	s_add_u32 s24, s24, 0x100
	s_addc_u32 s25, s25, 0
	s_add_u32 s53, s53, 0x100
	s_addc_u32 s56, s56, 0
	s_cmp_gt_u32 s57, 41
	s_barrier
	s_cbranch_scc0 .LBB0_314
	s_and_b64 vcc, exec, s[16:17]
	s_cbranch_vccz .LBB0_317
	s_barrier

; #define PG8_STAGE(bufoff, gbase, voff) do { _Pragma("unroll") for (int _i = 0; _i < 2; ++_i) \
;         __builtin_amdgcn_global_load_lds((const unsigned*)((const char*)(gbase) + (voff)[_i]), (PG8_LAS unsigned*)(lds + (bufoff) + ldsw + _i * 8192), 16, 0, 0); } while (0)
; #define PG8_LDA(dst, b, h) do { _Pragma("unroll") for (int m = 0; m < 4; ++m) _Pragma("unroll") for (int k = 0; k < 2; ++k) dst[m][k] = *(const PG8_LAS bf16x8*)(lds + PG8_SA(b, h) + aoff + m * 2048 + k * 1024); } while (0)
; #define PG8_LDB(dst, b, h) do { _Pragma("unroll") for (int n = 0; n < 2; ++n) _Pragma("unroll") for (int k = 0; k < 2; ++k) dst[n][k] = *(const PG8_LAS bf16x8*)(lds + PG8_SB(b, h) + boff + n * 2048 + k * 1024); } while (0)
; #define PG8_MMA(ai, bj, At, Bt) do { __builtin_amdgcn_s_setprio(1); _Pragma("unroll") for (int m = 0; m < 4; ++m) _Pragma("unroll") for (int n = 0; n < 2; ++n) _Pragma("unroll") for (int k = 0; k < 2; ++k) \
;         acc[ai][bj][m][n] = __builtin_amdgcn_mfma_f32_16x16x32_bf16(Bt[n][k], At[m][k], acc[ai][bj][m][n], 0, 0, 0); __builtin_amdgcn_s_setprio(0); } while (0)
; #define PG8_WAIT_V(n) asm volatile("s_waitcnt vmcnt(" #n ")" ::: "memory")
; #define PG8_BAR __builtin_amdgcn_s_barrier()
; template <class Epi, class Sched, bool ALIGN_EPI = false, bool SP2 = false>
; __device__ __forceinline__ void gemm_phase(PG8_LAS unsigned char* lds, const Gemm g, const Sched& S, const Epi& E) {
;     ...
;         for (int t = 0; t < nt; t += 2) {
;             const bool last = (t == nt - 2);
;             const char* a1 = cA + (size_t)(t + 1) * kstep;
;             const char* a2 = last ? nA : cA + (size_t)(t + 2) * kstep; const char* b2 = last ? nB : cB + (size_t)(t + 2) * kstep;
;             const char* a3 = a2 + kstep; const char* b3 = b2 + kstep;
;             if (last && has_next) S.a_ready(nxt);
;             if constexpr (SP2) {
;             PG8_LDB(B0, 0, 0); PG8_LDB(B1, 0, 1); PG8_SCHED; PG8_LDA(At, 0, 0); PG8_STAGE(PG8_SA(1, 1), a1 + hstep, voffA);
;             PG8_WAIT_V(8); PG8_WAIT_L(0); PG8_BAR; PG8_MMA(0, 0, At, B0); PG8_MMA(0, 1, At, B1); PG8_BAR; PG8_SCHED;
;             PG8_LDA(At, 0, 1); PG8_STAGE(PG8_SB(0, 0), b2, voffB); PG8_STAGE(PG8_SB(0, 1), b2 + hstep, voffB); PG8_STAGE(PG8_SA(0, 0), a2, voffA);
;             PG8_WAIT_V(8); PG8_WAIT_L(0); PG8_BAR; PG8_MMA(1, 0, At, B0); PG8_MMA(1, 1, At, B1); PG8_BAR; PG8_SCHED;
.LBB0_410:
	ds_read_b128 v[144:147], v155
	ds_read_b128 v[160:163], v155 offset:1024
	ds_read_b128 v[164:167], v155 offset:2048
	ds_read_b128 v[168:171], v155 offset:3072
	ds_read_b128 v[172:175], v156
	ds_read_b128 v[176:179], v156 offset:1024
	ds_read_b128 v[180:183], v156 offset:2048
	ds_read_b128 v[184:187], v156 offset:3072
	s_add_u32 s22, s18, 0xfffc0080
	s_addc_u32 s23, s19, -1
	s_cmp_eq_u32 s50, 12
	s_cselect_b32 s25, s11, s23
	s_cselect_b32 s24, s46, s22
	s_cselect_b32 s23, s9, s49
	s_cselect_b32 s22, s47, s48
	v_lshl_add_u64 v[148:149], s[18:19], 0, v[136:137]
	s_add_i32 m0, s17, 0xc000
	ds_read_b128 v[188:191], v157
	ds_read_b128 v[192:195], v157 offset:1024
	ds_read_b128 v[196:199], v157 offset:2048
	ds_read_b128 v[200:203], v157 offset:3072
	ds_read_b128 v[204:207], v157 offset:4096
	ds_read_b128 v[210:213], v157 offset:5120
	ds_read_b128 v[214:217], v157 offset:6144
	ds_read_b128 v[218:221], v157 offset:7168
	global_load_lds_dwordx4 v[148:149], off
	v_lshl_add_u64 v[148:149], s[18:19], 0, v[138:139]
	s_add_i32 m0, s17, 0xe000
	s_nop 0
	global_load_lds_dwordx4 v[148:149], off
	s_waitcnt vmcnt(8)
	s_waitcnt lgkmcnt(0)
	s_barrier
	s_setprio 1
	s_waitcnt lgkmcnt(0)
	v_mfma_f32_16x16x32_bf16 v[124:127], v[144:147], v[188:191], v[124:127]
	v_mfma_f32_16x16x32_bf16 v[120:123], v[164:167], v[188:191], v[120:123]
	v_mfma_f32_16x16x32_bf16 v[108:111], v[144:147], v[196:199], v[108:111]
	v_mfma_f32_16x16x32_bf16 v[104:107], v[164:167], v[196:199], v[104:107]
	v_mfma_f32_16x16x32_bf16 v[92:95], v[144:147], v[204:207], v[92:95]
	v_mfma_f32_16x16x32_bf16 v[88:91], v[164:167], v[204:207], v[88:91]
	v_mfma_f32_16x16x32_bf16 v[84:87], v[144:147], v[214:217], v[84:87]
	v_mfma_f32_16x16x32_bf16 v[76:79], v[164:167], v[214:217], v[76:79]
	v_mfma_f32_16x16x32_bf16 v[124:127], v[160:163], v[192:195], v[124:127]
	v_mfma_f32_16x16x32_bf16 v[120:123], v[168:171], v[192:195], v[120:123]
	v_mfma_f32_16x16x32_bf16 v[108:111], v[160:163], v[200:203], v[108:111]
	v_mfma_f32_16x16x32_bf16 v[104:107], v[168:171], v[200:203], v[104:107]
	v_mfma_f32_16x16x32_bf16 v[92:95], v[160:163], v[210:213], v[92:95]
	v_mfma_f32_16x16x32_bf16 v[88:91], v[168:171], v[210:213], v[88:91]
	v_mfma_f32_16x16x32_bf16 v[84:87], v[160:163], v[218:221], v[84:87]
	v_mfma_f32_16x16x32_bf16 v[76:79], v[168:171], v[218:221], v[76:79]
	s_setprio 0
	s_setprio 1
	v_mfma_f32_16x16x32_bf16 v[116:119], v[172:175], v[188:191], v[116:119]
	v_mfma_f32_16x16x32_bf16 v[112:115], v[180:183], v[188:191], v[112:115]
	v_mfma_f32_16x16x32_bf16 v[100:103], v[172:175], v[196:199], v[100:103]
	v_mfma_f32_16x16x32_bf16 v[96:99], v[180:183], v[196:199], v[96:99]
	v_mfma_f32_16x16x32_bf16 v[80:83], v[172:175], v[204:207], v[80:83]
	v_mfma_f32_16x16x32_bf16 v[72:75], v[180:183], v[204:207], v[72:75]
	v_mfma_f32_16x16x32_bf16 v[68:71], v[172:175], v[214:217], v[68:71]
	v_mfma_f32_16x16x32_bf16 v[64:67], v[180:183], v[214:217], v[64:67]
	v_mfma_f32_16x16x32_bf16 v[116:119], v[176:179], v[192:195], v[116:119]
	v_mfma_f32_16x16x32_bf16 v[112:115], v[184:187], v[192:195], v[112:115]
	v_mfma_f32_16x16x32_bf16 v[100:103], v[176:179], v[200:203], v[100:103]
	v_mfma_f32_16x16x32_bf16 v[96:99], v[184:187], v[200:203], v[96:99]
	v_mfma_f32_16x16x32_bf16 v[80:83], v[176:179], v[210:213], v[80:83]
	v_mfma_f32_16x16x32_bf16 v[72:75], v[184:187], v[210:213], v[72:75]
	v_mfma_f32_16x16x32_bf16 v[68:71], v[176:179], v[218:221], v[68:71]
	v_mfma_f32_16x16x32_bf16 v[64:67], v[184:187], v[218:221], v[64:67]
	s_setprio 0
	s_barrier
	s_add_i32 s51, s43, s30
	v_lshl_add_u64 v[148:149], s[22:23], 0, v[130:131]
	s_mov_b32 m0, s51
	ds_read_b128 v[188:191], v157 offset:16384
	ds_read_b128 v[192:195], v157 offset:17408
	ds_read_b128 v[196:199], v157 offset:18432
	ds_read_b128 v[200:203], v157 offset:19456
	ds_read_b128 v[204:207], v157 offset:20480
	ds_read_b128 v[210:213], v157 offset:21504
	ds_read_b128 v[214:217], v157 offset:22528
	ds_read_b128 v[218:221], v157 offset:23552
	global_load_lds_dwordx4 v[148:149], off
	s_add_i32 m0, s51, 0x2000
	s_add_u32 s52, s22, 0x40000
	v_lshl_add_u64 v[222:223], s[22:23], 0, v[134:135]
	s_addc_u32 s53, s23, 0
	s_add_i32 s51, s44, s30
	global_load_lds_dwordx4 v[222:223], off
	v_lshl_add_u64 v[224:225], s[52:53], 0, v[130:131]
	s_mov_b32 m0, s51
	v_lshl_add_u64 v[226:227], s[24:25], 0, v[132:133]
	global_load_lds_dwordx4 v[224:225], off
	v_lshl_add_u64 v[224:225], s[52:53], 0, v[134:135]
	s_add_i32 m0, s51, 0x2000
	s_nop 0
	global_load_lds_dwordx4 v[224:225], off
	v_lshl_add_u64 v[224:225], s[24:25], 0, v[128:129]
	s_mov_b32 m0, s17
	s_nop 0
	global_load_lds_dwordx4 v[224:225], off
	s_mov_b32 m0, s35
	s_nop 0
	global_load_lds_dwordx4 v[226:227], off
	s_waitcnt vmcnt(8)
	s_waitcnt lgkmcnt(0)
	s_barrier
; #define PG8_STAGE(bufoff, gbase, voff) do { _Pragma("unroll") for (int _i = 0; _i < 2; ++_i) \
;         __builtin_amdgcn_global_load_lds((const unsigned*)((const char*)(gbase) + (voff)[_i]), (PG8_LAS unsigned*)(lds + (bufoff) + ldsw + _i * 8192), 16, 0, 0); } while (0)
; #define PG8_LDA(dst, b, h) do { _Pragma("unroll") for (int m = 0; m < 4; ++m) _Pragma("unroll") for (int k = 0; k < 2; ++k) dst[m][k] = *(const PG8_LAS bf16x8*)(lds + PG8_SA(b, h) + aoff + m * 2048 + k * 1024); } while (0)
; #define PG8_LDB(dst, b, h) do { _Pragma("unroll") for (int n = 0; n < 2; ++n) _Pragma("unroll") for (int k = 0; k < 2; ++k) dst[n][k] = *(const PG8_LAS bf16x8*)(lds + PG8_SB(b, h) + boff + n * 2048 + k * 1024); } while (0)
; #define PG8_MMA(ai, bj, At, Bt) do { __builtin_amdgcn_s_setprio(1); _Pragma("unroll") for (int m = 0; m < 4; ++m) _Pragma("unroll") for (int n = 0; n < 2; ++n) _Pragma("unroll") for (int k = 0; k < 2; ++k) \
;         acc[ai][bj][m][n] = __builtin_amdgcn_mfma_f32_16x16x32_bf16(Bt[n][k], At[m][k], acc[ai][bj][m][n], 0, 0, 0); __builtin_amdgcn_s_setprio(0); } while (0)
; #define PG8_WAIT_V(n) asm volatile("s_waitcnt vmcnt(" #n ")" ::: "memory")
; #define PG8_WAIT_L(n) asm volatile("s_waitcnt lgkmcnt(" #n ")" ::: "memory")
; #define PG8_BAR __builtin_amdgcn_s_barrier()
; #define PG8_SCHED __builtin_amdgcn_sched_barrier(0)
; template <class Epi, class Sched, bool ALIGN_EPI = false, bool SP2 = false>
; __device__ __forceinline__ void gemm_phase(PG8_LAS unsigned char* lds, const Gemm g, const Sched& S, const Epi& E) {
;     ...
;             PG8_WAIT_V(8); PG8_WAIT_L(0); PG8_BAR; PG8_MMA(1, 0, At, B0); PG8_MMA(1, 1, At, B1); PG8_BAR; PG8_SCHED;
;             PG8_LDB(B0, 1, 0); PG8_LDB(B1, 1, 1); PG8_SCHED; PG8_LDA(At, 1, 0); PG8_STAGE(PG8_SA(0, 1), a2 + hstep, voffA);
;             PG8_WAIT_V(8); PG8_WAIT_L(0); PG8_BAR; PG8_MMA(0, 0, At, B0); PG8_MMA(0, 1, At, B1); PG8_BAR; PG8_SCHED;
	s_setprio 1
	s_waitcnt lgkmcnt(0)
	v_mfma_f32_16x16x32_bf16 v[60:63], v[144:147], v[188:191], v[60:63]
	v_mfma_f32_16x16x32_bf16 v[56:59], v[164:167], v[188:191], v[56:59]
	v_mfma_f32_16x16x32_bf16 v[44:47], v[144:147], v[196:199], v[44:47]
	v_mfma_f32_16x16x32_bf16 v[40:43], v[164:167], v[196:199], v[40:43]
	v_mfma_f32_16x16x32_bf16 v[28:31], v[144:147], v[204:207], v[28:31]
	v_mfma_f32_16x16x32_bf16 v[24:27], v[164:167], v[204:207], v[24:27]
	v_mfma_f32_16x16x32_bf16 v[12:15], v[144:147], v[214:217], v[12:15]
	v_mfma_f32_16x16x32_bf16 v[8:11], v[164:167], v[214:217], v[8:11]
	v_mfma_f32_16x16x32_bf16 v[60:63], v[160:163], v[192:195], v[60:63]
	v_mfma_f32_16x16x32_bf16 v[56:59], v[168:171], v[192:195], v[56:59]
	v_mfma_f32_16x16x32_bf16 v[44:47], v[160:163], v[200:203], v[44:47]
	v_mfma_f32_16x16x32_bf16 v[40:43], v[168:171], v[200:203], v[40:43]
	v_mfma_f32_16x16x32_bf16 v[28:31], v[160:163], v[210:213], v[28:31]
	v_mfma_f32_16x16x32_bf16 v[24:27], v[168:171], v[210:213], v[24:27]
	v_mfma_f32_16x16x32_bf16 v[12:15], v[160:163], v[218:221], v[12:15]
	v_mfma_f32_16x16x32_bf16 v[8:11], v[168:171], v[218:221], v[8:11]
	s_setprio 0
	s_setprio 1
	v_mfma_f32_16x16x32_bf16 v[52:55], v[172:175], v[188:191], v[52:55]
	v_mfma_f32_16x16x32_bf16 v[48:51], v[180:183], v[188:191], v[48:51]
	v_mfma_f32_16x16x32_bf16 v[36:39], v[172:175], v[196:199], v[36:39]
	v_mfma_f32_16x16x32_bf16 v[32:35], v[180:183], v[196:199], v[32:35]
	v_mfma_f32_16x16x32_bf16 v[20:23], v[172:175], v[204:207], v[20:23]
	v_mfma_f32_16x16x32_bf16 v[16:19], v[180:183], v[204:207], v[16:19]
	v_mfma_f32_16x16x32_bf16 v[4:7], v[172:175], v[214:217], v[4:7]
	v_mfma_f32_16x16x32_bf16 v[0:3], v[180:183], v[214:217], v[0:3]
	v_mfma_f32_16x16x32_bf16 v[52:55], v[176:179], v[192:195], v[52:55]
	v_mfma_f32_16x16x32_bf16 v[48:51], v[184:187], v[192:195], v[48:51]
	v_mfma_f32_16x16x32_bf16 v[36:39], v[176:179], v[200:203], v[36:39]
	v_mfma_f32_16x16x32_bf16 v[32:35], v[184:187], v[200:203], v[32:35]
	v_mfma_f32_16x16x32_bf16 v[20:23], v[176:179], v[210:213], v[20:23]
	v_mfma_f32_16x16x32_bf16 v[16:19], v[184:187], v[210:213], v[16:19]
	v_mfma_f32_16x16x32_bf16 v[4:7], v[176:179], v[218:221], v[4:7]
	v_mfma_f32_16x16x32_bf16 v[0:3], v[184:187], v[218:221], v[0:3]
	s_setprio 0
	s_barrier
	s_add_i32 s51, 0, 0x18000
	v_add_u32_e32 v159, s51, v153
	s_add_i32 s52, 0, 0x1c000
	ds_read_b128 v[144:147], v159
	ds_read_b128 v[160:163], v159 offset:1024
	ds_read_b128 v[164:167], v159 offset:2048
	ds_read_b128 v[168:171], v159 offset:3072
	v_add_u32_e32 v159, s52, v153
	ds_read_b128 v[172:175], v159
	ds_read_b128 v[176:179], v159 offset:1024
	ds_read_b128 v[180:183], v159 offset:2048
	ds_read_b128 v[184:187], v159 offset:3072
	s_add_u32 s24, s24, 0x40000
	s_addc_u32 s25, s25, 0
	s_mov_b32 m0, s36
	v_lshl_add_u64 v[228:229], s[24:25], 0, v[128:129]
	ds_read_b128 v[188:191], v157 offset:32768
	ds_read_b128 v[192:195], v157 offset:33792
	ds_read_b128 v[196:199], v157 offset:34816
	ds_read_b128 v[200:203], v157 offset:35840
	ds_read_b128 v[204:207], v157 offset:36864
	ds_read_b128 v[210:213], v157 offset:37888
	ds_read_b128 v[214:217], v157 offset:38912
	ds_read_b128 v[218:221], v157 offset:39936
	global_load_lds_dwordx4 v[228:229], off
	v_lshl_add_u64 v[228:229], s[24:25], 0, v[132:133]
	s_mov_b32 m0, s37
	s_nop 0
	global_load_lds_dwordx4 v[228:229], off
	s_waitcnt vmcnt(8)
	s_waitcnt lgkmcnt(0)
	s_barrier
	s_setprio 1
	s_waitcnt lgkmcnt(0)
	v_mfma_f32_16x16x32_bf16 v[124:127], v[144:147], v[188:191], v[124:127]
	v_mfma_f32_16x16x32_bf16 v[120:123], v[164:167], v[188:191], v[120:123]
	v_mfma_f32_16x16x32_bf16 v[108:111], v[144:147], v[196:199], v[108:111]
	v_mfma_f32_16x16x32_bf16 v[104:107], v[164:167], v[196:199], v[104:107]
	v_mfma_f32_16x16x32_bf16 v[92:95], v[144:147], v[204:207], v[92:95]
	v_mfma_f32_16x16x32_bf16 v[88:91], v[164:167], v[204:207], v[88:91]
	v_mfma_f32_16x16x32_bf16 v[84:87], v[144:147], v[214:217], v[84:87]
	v_mfma_f32_16x16x32_bf16 v[76:79], v[164:167], v[214:217], v[76:79]
	v_mfma_f32_16x16x32_bf16 v[124:127], v[160:163], v[192:195], v[124:127]
	v_mfma_f32_16x16x32_bf16 v[120:123], v[168:171], v[192:195], v[120:123]
	v_mfma_f32_16x16x32_bf16 v[108:111], v[160:163], v[200:203], v[108:111]
	v_mfma_f32_16x16x32_bf16 v[104:107], v[168:171], v[200:203], v[104:107]
	v_mfma_f32_16x16x32_bf16 v[92:95], v[160:163], v[210:213], v[92:95]
	v_mfma_f32_16x16x32_bf16 v[88:91], v[168:171], v[210:213], v[88:91]
	v_mfma_f32_16x16x32_bf16 v[84:87], v[160:163], v[218:221], v[84:87]
	v_mfma_f32_16x16x32_bf16 v[76:79], v[168:171], v[218:221], v[76:79]
	s_setprio 0
	s_setprio 1
	v_mfma_f32_16x16x32_bf16 v[116:119], v[172:175], v[188:191], v[116:119]
	v_mfma_f32_16x16x32_bf16 v[112:115], v[180:183], v[188:191], v[112:115]
	v_mfma_f32_16x16x32_bf16 v[100:103], v[172:175], v[196:199], v[100:103]
	v_mfma_f32_16x16x32_bf16 v[96:99], v[180:183], v[196:199], v[96:99]
	v_mfma_f32_16x16x32_bf16 v[80:83], v[172:175], v[204:207], v[80:83]
	v_mfma_f32_16x16x32_bf16 v[72:75], v[180:183], v[204:207], v[72:75]
	v_mfma_f32_16x16x32_bf16 v[68:71], v[172:175], v[214:217], v[68:71]
	v_mfma_f32_16x16x32_bf16 v[64:67], v[180:183], v[214:217], v[64:67]
	v_mfma_f32_16x16x32_bf16 v[116:119], v[176:179], v[192:195], v[116:119]
	v_mfma_f32_16x16x32_bf16 v[112:115], v[184:187], v[192:195], v[112:115]
	v_mfma_f32_16x16x32_bf16 v[100:103], v[176:179], v[200:203], v[100:103]
	v_mfma_f32_16x16x32_bf16 v[96:99], v[184:187], v[200:203], v[96:99]
	v_mfma_f32_16x16x32_bf16 v[80:83], v[176:179], v[210:213], v[80:83]
	v_mfma_f32_16x16x32_bf16 v[72:75], v[184:187], v[210:213], v[72:75]
	v_mfma_f32_16x16x32_bf16 v[68:71], v[176:179], v[218:221], v[68:71]
	v_mfma_f32_16x16x32_bf16 v[64:67], v[184:187], v[218:221], v[64:67]
	s_setprio 0
	s_barrier
; #define PG8_STAGE(bufoff, gbase, voff) do { _Pragma("unroll") for (int _i = 0; _i < 2; ++_i) \
;         __builtin_amdgcn_global_load_lds((const unsigned*)((const char*)(gbase) + (voff)[_i]), (PG8_LAS unsigned*)(lds + (bufoff) + ldsw + _i * 8192), 16, 0, 0); } while (0)
; #define PG8_LDA(dst, b, h) do { _Pragma("unroll") for (int m = 0; m < 4; ++m) _Pragma("unroll") for (int k = 0; k < 2; ++k) dst[m][k] = *(const PG8_LAS bf16x8*)(lds + PG8_SA(b, h) + aoff + m * 2048 + k * 1024); } while (0)
; #define PG8_MMA(ai, bj, At, Bt) do { __builtin_amdgcn_s_setprio(1); _Pragma("unroll") for (int m = 0; m < 4; ++m) _Pragma("unroll") for (int n = 0; n < 2; ++n) _Pragma("unroll") for (int k = 0; k < 2; ++k) \
;         acc[ai][bj][m][n] = __builtin_amdgcn_mfma_f32_16x16x32_bf16(Bt[n][k], At[m][k], acc[ai][bj][m][n], 0, 0, 0); __builtin_amdgcn_s_setprio(0); } while (0)
; #define PG8_WAIT_V(n) asm volatile("s_waitcnt vmcnt(" #n ")" ::: "memory")
; #define PG8_WAIT_L(n) asm volatile("s_waitcnt lgkmcnt(" #n ")" ::: "memory")
; #define PG8_BAR __builtin_amdgcn_s_barrier()
; #define PG8_SCHED __builtin_amdgcn_sched_barrier(0)
; template <class Epi, class Sched, bool ALIGN_EPI = false, bool SP2 = false>
; __device__ __forceinline__ void gemm_phase(PG8_LAS unsigned char* lds, const Gemm g, const Sched& S, const Epi& E) {
;     ...
;         for (int t = 0; t < nt; t += 2) {
;             const bool last = (t == nt - 2);
;             const char* a1 = cA + (size_t)(t + 1) * kstep;
;             const char* a2 = last ? nA : cA + (size_t)(t + 2) * kstep; const char* b2 = last ? nB : cB + (size_t)(t + 2) * kstep;
;             const char* a3 = a2 + kstep; const char* b3 = b2 + kstep;
;     ...
;             PG8_LDA(At, 1, 1); PG8_STAGE(PG8_SB(1, 0), b3, voffB); PG8_STAGE(PG8_SB(1, 1), b3 + hstep, voffB); PG8_STAGE(PG8_SA(1, 0), a3, voffA);
;             PG8_WAIT_V(8); PG8_WAIT_L(0); PG8_BAR; PG8_MMA(1, 0, At, B0); PG8_MMA(1, 1, At, B1); PG8_BAR; PG8_SCHED;
	s_add_i32 s24, s51, s30
	v_lshl_add_u64 v[148:149], v[148:149], 0, s[4:5]
	s_mov_b32 m0, s24
	ds_read_b128 v[188:191], v157 offset:49152
	ds_read_b128 v[192:195], v157 offset:50176
	ds_read_b128 v[196:199], v157 offset:51200
	ds_read_b128 v[200:203], v157 offset:52224
	ds_read_b128 v[204:207], v157 offset:53248
	ds_read_b128 v[210:213], v157 offset:54272
	ds_read_b128 v[214:217], v157 offset:55296
	ds_read_b128 v[218:221], v157 offset:56320
	global_load_lds_dwordx4 v[148:149], off
	s_add_i32 m0, s24, 0x2000
	s_add_u32 s22, s22, 0x40080
	v_lshl_add_u64 v[148:149], v[222:223], 0, s[4:5]
	s_addc_u32 s23, s23, 0
	s_add_i32 s24, s52, s30
	global_load_lds_dwordx4 v[148:149], off
	v_lshl_add_u64 v[148:149], s[22:23], 0, v[130:131]
	s_mov_b32 m0, s24
	s_nop 0
	global_load_lds_dwordx4 v[148:149], off
	v_lshl_add_u64 v[148:149], s[22:23], 0, v[134:135]
	s_add_i32 m0, s24, 0x2000
	s_nop 0
	global_load_lds_dwordx4 v[148:149], off
	v_lshl_add_u64 v[148:149], v[224:225], 0, s[4:5]
	s_mov_b32 m0, s40
	s_nop 0
	global_load_lds_dwordx4 v[148:149], off
	v_lshl_add_u64 v[148:149], v[226:227], 0, s[4:5]
	s_mov_b32 m0, s41
	s_nop 0
	global_load_lds_dwordx4 v[148:149], off
	s_waitcnt vmcnt(8)
	s_waitcnt lgkmcnt(0)
	s_barrier
	s_setprio 1
	s_waitcnt lgkmcnt(0)
	v_mfma_f32_16x16x32_bf16 v[60:63], v[144:147], v[188:191], v[60:63]
	v_mfma_f32_16x16x32_bf16 v[56:59], v[164:167], v[188:191], v[56:59]
	v_mfma_f32_16x16x32_bf16 v[44:47], v[144:147], v[196:199], v[44:47]
	v_mfma_f32_16x16x32_bf16 v[40:43], v[164:167], v[196:199], v[40:43]
	v_mfma_f32_16x16x32_bf16 v[28:31], v[144:147], v[204:207], v[28:31]
	v_mfma_f32_16x16x32_bf16 v[24:27], v[164:167], v[204:207], v[24:27]
	v_mfma_f32_16x16x32_bf16 v[12:15], v[144:147], v[214:217], v[12:15]
	v_mfma_f32_16x16x32_bf16 v[8:11], v[164:167], v[214:217], v[8:11]
	v_mfma_f32_16x16x32_bf16 v[60:63], v[160:163], v[192:195], v[60:63]
	v_mfma_f32_16x16x32_bf16 v[56:59], v[168:171], v[192:195], v[56:59]
	v_mfma_f32_16x16x32_bf16 v[44:47], v[160:163], v[200:203], v[44:47]
	v_mfma_f32_16x16x32_bf16 v[40:43], v[168:171], v[200:203], v[40:43]
	v_mfma_f32_16x16x32_bf16 v[28:31], v[160:163], v[210:213], v[28:31]
	v_mfma_f32_16x16x32_bf16 v[24:27], v[168:171], v[210:213], v[24:27]
	v_mfma_f32_16x16x32_bf16 v[12:15], v[160:163], v[218:221], v[12:15]
	v_mfma_f32_16x16x32_bf16 v[8:11], v[168:171], v[218:221], v[8:11]
	s_setprio 0
	s_setprio 1
	v_mfma_f32_16x16x32_bf16 v[52:55], v[172:175], v[188:191], v[52:55]
	v_mfma_f32_16x16x32_bf16 v[48:51], v[180:183], v[188:191], v[48:51]
	v_mfma_f32_16x16x32_bf16 v[36:39], v[172:175], v[196:199], v[36:39]
	v_mfma_f32_16x16x32_bf16 v[32:35], v[180:183], v[196:199], v[32:35]
	v_mfma_f32_16x16x32_bf16 v[20:23], v[172:175], v[204:207], v[20:23]
	v_mfma_f32_16x16x32_bf16 v[16:19], v[180:183], v[204:207], v[16:19]
	v_mfma_f32_16x16x32_bf16 v[4:7], v[172:175], v[214:217], v[4:7]
	v_mfma_f32_16x16x32_bf16 v[0:3], v[180:183], v[214:217], v[0:3]
	v_mfma_f32_16x16x32_bf16 v[52:55], v[176:179], v[192:195], v[52:55]
	v_mfma_f32_16x16x32_bf16 v[48:51], v[184:187], v[192:195], v[48:51]
	v_mfma_f32_16x16x32_bf16 v[36:39], v[176:179], v[200:203], v[36:39]
	v_mfma_f32_16x16x32_bf16 v[32:35], v[184:187], v[200:203], v[32:35]
	v_mfma_f32_16x16x32_bf16 v[20:23], v[176:179], v[210:213], v[20:23]
	v_mfma_f32_16x16x32_bf16 v[16:19], v[184:187], v[210:213], v[16:19]
	v_mfma_f32_16x16x32_bf16 v[4:7], v[176:179], v[218:221], v[4:7]
	v_mfma_f32_16x16x32_bf16 v[0:3], v[184:187], v[218:221], v[0:3]
	s_setprio 0
	s_add_i32 s50, s50, 2
	s_add_u32 s18, s18, 0x100
	s_addc_u32 s19, s19, 0
	s_add_u32 s48, s48, 0x100
	s_addc_u32 s49, s49, 0
	s_cmp_gt_u32 s50, 13
	s_barrier
	s_cbranch_scc0 .LBB0_410
	s_and_b64 vcc, exec, s[6:7]
	s_cbranch_vccz .LBB0_413
	s_barrier

; #define PG8_STAGE(bufoff, gbase, voff) do { _Pragma("unroll") for (int _i = 0; _i < 2; ++_i) \
;         __builtin_amdgcn_global_load_lds((const unsigned*)((const char*)(gbase) + (voff)[_i]), (PG8_LAS unsigned*)(lds + (bufoff) + ldsw + _i * 8192), 16, 0, 0); } while (0)
; #define PG8_LDA(dst, b, h) do { _Pragma("unroll") for (int m = 0; m < 4; ++m) _Pragma("unroll") for (int k = 0; k < 2; ++k) dst[m][k] = *(const PG8_LAS bf16x8*)(lds + PG8_SA(b, h) + aoff + m * 2048 + k * 1024); } while (0)
; #define PG8_MMA(ai, bj, At, Bt) do { __builtin_amdgcn_s_setprio(1); _Pragma("unroll") for (int m = 0; m < 4; ++m) _Pragma("unroll") for (int n = 0; n < 2; ++n) _Pragma("unroll") for (int k = 0; k < 2; ++k) \
;         acc[ai][bj][m][n] = __builtin_amdgcn_mfma_f32_16x16x32_bf16(Bt[n][k], At[m][k], acc[ai][bj][m][n], 0, 0, 0); __builtin_amdgcn_s_setprio(0); } while (0)
; #define PG8_WAIT_V(n) asm volatile("s_waitcnt vmcnt(" #n ")" ::: "memory")
; #define PG8_WAIT_L(n) asm volatile("s_waitcnt lgkmcnt(" #n ")" ::: "memory")
; #define PG8_BAR __builtin_amdgcn_s_barrier()
; #define PG8_SCHED __builtin_amdgcn_sched_barrier(0)
; template <class Epi, class Sched, bool ALIGN_EPI = false, bool SP2 = false>
; __device__ __forceinline__ void gemm_phase(PG8_LAS unsigned char* lds, const Gemm g, const Sched& S, const Epi& E) {
;     ...
;             PG8_WAIT_V(8); PG8_WAIT_L(0); PG8_BAR; PG8_MMA(0, 0, At, B0); PG8_MMA(0, 1, At, B1); PG8_BAR; PG8_SCHED;
;             PG8_LDA(At, 0, 1); PG8_STAGE(PG8_SB(0, 0), b2, voffB); PG8_STAGE(PG8_SB(0, 1), b2 + hstep, voffB); PG8_STAGE(PG8_SA(0, 0), a2, voffA);
;             PG8_WAIT_V(8); PG8_WAIT_L(0); PG8_BAR; PG8_MMA(1, 0, At, B0); PG8_MMA(1, 1, At, B1); PG8_BAR; PG8_SCHED;
.Lmy_pf10_skip:
	s_setprio 1
	s_waitcnt lgkmcnt(0)
	v_mfma_f32_16x16x32_bf16 v[124:127], v[144:147], v[184:187], v[124:127]
	v_mfma_f32_16x16x32_bf16 v[120:123], v[160:163], v[184:187], v[120:123]
	v_mfma_f32_16x16x32_bf16 v[108:111], v[144:147], v[192:195], v[108:111]
	v_mfma_f32_16x16x32_bf16 v[104:107], v[160:163], v[192:195], v[104:107]
	v_mfma_f32_16x16x32_bf16 v[92:95], v[144:147], v[200:203], v[92:95]
	v_mfma_f32_16x16x32_bf16 v[88:91], v[160:163], v[200:203], v[88:91]
	v_mfma_f32_16x16x32_bf16 v[76:79], v[144:147], v[210:213], v[76:79]
	v_mfma_f32_16x16x32_bf16 v[72:75], v[160:163], v[210:213], v[72:75]
	v_mfma_f32_16x16x32_bf16 v[124:127], v[156:159], v[188:191], v[124:127]
	v_mfma_f32_16x16x32_bf16 v[120:123], v[164:167], v[188:191], v[120:123]
	v_mfma_f32_16x16x32_bf16 v[108:111], v[156:159], v[196:199], v[108:111]
	v_mfma_f32_16x16x32_bf16 v[104:107], v[164:167], v[196:199], v[104:107]
	v_mfma_f32_16x16x32_bf16 v[92:95], v[156:159], v[204:207], v[92:95]
	v_mfma_f32_16x16x32_bf16 v[88:91], v[164:167], v[204:207], v[88:91]
	v_mfma_f32_16x16x32_bf16 v[76:79], v[156:159], v[214:217], v[76:79]
	v_mfma_f32_16x16x32_bf16 v[72:75], v[164:167], v[214:217], v[72:75]
	s_setprio 0
	s_setprio 1
	v_mfma_f32_16x16x32_bf16 v[116:119], v[168:171], v[184:187], v[116:119]
	v_mfma_f32_16x16x32_bf16 v[112:115], v[176:179], v[184:187], v[112:115]
	v_mfma_f32_16x16x32_bf16 v[100:103], v[168:171], v[192:195], v[100:103]
	v_mfma_f32_16x16x32_bf16 v[96:99], v[176:179], v[192:195], v[96:99]
	v_mfma_f32_16x16x32_bf16 v[84:87], v[168:171], v[200:203], v[84:87]
	v_mfma_f32_16x16x32_bf16 v[80:83], v[176:179], v[200:203], v[80:83]
	v_mfma_f32_16x16x32_bf16 v[68:71], v[168:171], v[210:213], v[68:71]
	v_mfma_f32_16x16x32_bf16 v[64:67], v[176:179], v[210:213], v[64:67]
	v_mfma_f32_16x16x32_bf16 v[116:119], v[172:175], v[188:191], v[116:119]
	v_mfma_f32_16x16x32_bf16 v[112:115], v[180:183], v[188:191], v[112:115]
	v_mfma_f32_16x16x32_bf16 v[100:103], v[172:175], v[196:199], v[100:103]
	v_mfma_f32_16x16x32_bf16 v[96:99], v[180:183], v[196:199], v[96:99]
	v_mfma_f32_16x16x32_bf16 v[84:87], v[172:175], v[204:207], v[84:87]
	v_mfma_f32_16x16x32_bf16 v[80:83], v[180:183], v[204:207], v[80:83]
	v_mfma_f32_16x16x32_bf16 v[68:71], v[172:175], v[214:217], v[68:71]
	v_mfma_f32_16x16x32_bf16 v[64:67], v[180:183], v[214:217], v[64:67]
	s_setprio 0
	s_barrier
	s_add_i32 s54, s48, s38
	v_lshl_add_u64 v[218:219], s[28:29], 0, v[130:131]
	s_mov_b32 m0, s54
	ds_read_b128 v[184:187], v153 offset:16384
	ds_read_b128 v[188:191], v153 offset:17408
	ds_read_b128 v[192:195], v153 offset:18432
	ds_read_b128 v[196:199], v153 offset:19456
	ds_read_b128 v[200:203], v153 offset:20480
	ds_read_b128 v[204:207], v153 offset:21504
	ds_read_b128 v[210:213], v153 offset:22528
	ds_read_b128 v[214:217], v153 offset:23552
	global_load_lds_dwordx4 v[218:219], off
	s_add_i32 m0, s54, 0x2000
	s_add_u32 s54, s28, 0x40000
	v_lshl_add_u64 v[220:221], s[28:29], 0, v[134:135]
	s_addc_u32 s55, s29, 0
	s_add_i32 s56, s49, s38
	global_load_lds_dwordx4 v[220:221], off
	v_lshl_add_u64 v[222:223], s[54:55], 0, v[130:131]
	s_mov_b32 m0, s56
	v_lshl_add_u64 v[224:225], s[30:31], 0, v[132:133]
	global_load_lds_dwordx4 v[222:223], off
	v_lshl_add_u64 v[222:223], s[54:55], 0, v[134:135]
	s_add_i32 m0, s56, 0x2000
	s_nop 0
	global_load_lds_dwordx4 v[222:223], off
	v_lshl_add_u64 v[222:223], s[30:31], 0, v[128:129]
	s_mov_b32 m0, s25
	s_nop 0
	global_load_lds_dwordx4 v[222:223], off
	s_mov_b32 m0, s39
	s_nop 0
	global_load_lds_dwordx4 v[224:225], off
	s_waitcnt vmcnt(8)
	s_waitcnt lgkmcnt(0)
	s_barrier
	s_setprio 1
	s_waitcnt lgkmcnt(0)
	v_mfma_f32_16x16x32_bf16 v[60:63], v[144:147], v[184:187], v[60:63]
	v_mfma_f32_16x16x32_bf16 v[56:59], v[160:163], v[184:187], v[56:59]
	v_mfma_f32_16x16x32_bf16 v[44:47], v[144:147], v[192:195], v[44:47]
	v_mfma_f32_16x16x32_bf16 v[40:43], v[160:163], v[192:195], v[40:43]
	v_mfma_f32_16x16x32_bf16 v[28:31], v[144:147], v[200:203], v[28:31]
	v_mfma_f32_16x16x32_bf16 v[24:27], v[160:163], v[200:203], v[24:27]
	v_mfma_f32_16x16x32_bf16 v[12:15], v[144:147], v[210:213], v[12:15]
	v_mfma_f32_16x16x32_bf16 v[8:11], v[160:163], v[210:213], v[8:11]
	v_mfma_f32_16x16x32_bf16 v[60:63], v[156:159], v[188:191], v[60:63]
	v_mfma_f32_16x16x32_bf16 v[56:59], v[164:167], v[188:191], v[56:59]
	v_mfma_f32_16x16x32_bf16 v[44:47], v[156:159], v[196:199], v[44:47]
	v_mfma_f32_16x16x32_bf16 v[40:43], v[164:167], v[196:199], v[40:43]
	v_mfma_f32_16x16x32_bf16 v[28:31], v[156:159], v[204:207], v[28:31]
	v_mfma_f32_16x16x32_bf16 v[24:27], v[164:167], v[204:207], v[24:27]
	v_mfma_f32_16x16x32_bf16 v[12:15], v[156:159], v[214:217], v[12:15]
	v_mfma_f32_16x16x32_bf16 v[8:11], v[164:167], v[214:217], v[8:11]
	s_setprio 0
	s_setprio 1
	v_mfma_f32_16x16x32_bf16 v[52:55], v[168:171], v[184:187], v[52:55]
	v_mfma_f32_16x16x32_bf16 v[48:51], v[176:179], v[184:187], v[48:51]
	v_mfma_f32_16x16x32_bf16 v[36:39], v[168:171], v[192:195], v[36:39]
	v_mfma_f32_16x16x32_bf16 v[32:35], v[176:179], v[192:195], v[32:35]
	v_mfma_f32_16x16x32_bf16 v[20:23], v[168:171], v[200:203], v[20:23]
	v_mfma_f32_16x16x32_bf16 v[16:19], v[176:179], v[200:203], v[16:19]
	v_mfma_f32_16x16x32_bf16 v[4:7], v[168:171], v[210:213], v[4:7]
	v_mfma_f32_16x16x32_bf16 v[0:3], v[176:179], v[210:213], v[0:3]
	v_mfma_f32_16x16x32_bf16 v[52:55], v[172:175], v[188:191], v[52:55]
	v_mfma_f32_16x16x32_bf16 v[48:51], v[180:183], v[188:191], v[48:51]
	v_mfma_f32_16x16x32_bf16 v[36:39], v[172:175], v[196:199], v[36:39]
	v_mfma_f32_16x16x32_bf16 v[32:35], v[180:183], v[196:199], v[32:35]
	v_mfma_f32_16x16x32_bf16 v[20:23], v[172:175], v[204:207], v[20:23]
	v_mfma_f32_16x16x32_bf16 v[16:19], v[180:183], v[204:207], v[16:19]
	v_mfma_f32_16x16x32_bf16 v[4:7], v[172:175], v[214:217], v[4:7]
	v_mfma_f32_16x16x32_bf16 v[0:3], v[180:183], v[214:217], v[0:3]
	s_setprio 0
	s_barrier
; #define PG8_STAGE(bufoff, gbase, voff) do { _Pragma("unroll") for (int _i = 0; _i < 2; ++_i) \
;         __builtin_amdgcn_global_load_lds((const unsigned*)((const char*)(gbase) + (voff)[_i]), (PG8_LAS unsigned*)(lds + (bufoff) + ldsw + _i * 8192), 16, 0, 0); } while (0)
; #define PG8_LDA(dst, b, h) do { _Pragma("unroll") for (int m = 0; m < 4; ++m) _Pragma("unroll") for (int k = 0; k < 2; ++k) dst[m][k] = *(const PG8_LAS bf16x8*)(lds + PG8_SA(b, h) + aoff + m * 2048 + k * 1024); } while (0)
; #define PG8_LDB(dst, b, h) do { _Pragma("unroll") for (int n = 0; n < 2; ++n) _Pragma("unroll") for (int k = 0; k < 2; ++k) dst[n][k] = *(const PG8_LAS bf16x8*)(lds + PG8_SB(b, h) + boff + n * 2048 + k * 1024); } while (0)
; #define PG8_MMA(ai, bj, At, Bt) do { __builtin_amdgcn_s_setprio(1); _Pragma("unroll") for (int m = 0; m < 4; ++m) _Pragma("unroll") for (int n = 0; n < 2; ++n) _Pragma("unroll") for (int k = 0; k < 2; ++k) \
;         acc[ai][bj][m][n] = __builtin_amdgcn_mfma_f32_16x16x32_bf16(Bt[n][k], At[m][k], acc[ai][bj][m][n], 0, 0, 0); __builtin_amdgcn_s_setprio(0); } while (0)
; #define PG8_WAIT_V(n) asm volatile("s_waitcnt vmcnt(" #n ")" ::: "memory")
; #define PG8_WAIT_L(n) asm volatile("s_waitcnt lgkmcnt(" #n ")" ::: "memory")
; #define PG8_BAR __builtin_amdgcn_s_barrier()
; #define PG8_SCHED __builtin_amdgcn_sched_barrier(0)
; template <class Epi, class Sched, bool ALIGN_EPI = false, bool SP2 = false>
; __device__ __forceinline__ void gemm_phase(PG8_LAS unsigned char* lds, const Gemm g, const Sched& S, const Epi& E) {
;     ...
;             PG8_LDB(B0, 1, 0); PG8_LDB(B1, 1, 1); PG8_SCHED; PG8_LDA(At, 1, 0); PG8_STAGE(PG8_SA(0, 1), a2 + hstep, voffA);
;             PG8_WAIT_V(8); PG8_WAIT_L(0); PG8_BAR; PG8_MMA(0, 0, At, B0); PG8_MMA(0, 1, At, B1); PG8_BAR; PG8_SCHED;
	s_add_i32 s54, 0, 0x18000
	v_add_u32_e32 v155, s54, v149
	s_add_i32 s55, 0, 0x1c000
	ds_read_b128 v[144:147], v155
	ds_read_b128 v[156:159], v155 offset:1024
	ds_read_b128 v[160:163], v155 offset:2048
	ds_read_b128 v[164:167], v155 offset:3072
	v_add_u32_e32 v155, s55, v149
	ds_read_b128 v[168:171], v155
	ds_read_b128 v[172:175], v155 offset:1024
	ds_read_b128 v[176:179], v155 offset:2048
	ds_read_b128 v[180:183], v155 offset:3072
	s_add_u32 s30, s30, 0x40000
	s_addc_u32 s31, s31, 0
	s_mov_b32 m0, s40
	v_lshl_add_u64 v[226:227], s[30:31], 0, v[128:129]
	ds_read_b128 v[184:187], v153 offset:32768
	ds_read_b128 v[188:191], v153 offset:33792
	ds_read_b128 v[192:195], v153 offset:34816
	ds_read_b128 v[196:199], v153 offset:35840
	ds_read_b128 v[200:203], v153 offset:36864
	ds_read_b128 v[204:207], v153 offset:37888
	ds_read_b128 v[210:213], v153 offset:38912
	ds_read_b128 v[214:217], v153 offset:39936
	global_load_lds_dwordx4 v[226:227], off
	v_lshl_add_u64 v[226:227], s[30:31], 0, v[132:133]
	s_mov_b32 m0, s41
	s_nop 0
	global_load_lds_dwordx4 v[226:227], off
	s_waitcnt vmcnt(8)
	s_waitcnt lgkmcnt(0)
	s_barrier
	s_setprio 1
	s_waitcnt lgkmcnt(0)
	v_mfma_f32_16x16x32_bf16 v[124:127], v[144:147], v[184:187], v[124:127]
	v_mfma_f32_16x16x32_bf16 v[120:123], v[160:163], v[184:187], v[120:123]
	v_mfma_f32_16x16x32_bf16 v[108:111], v[144:147], v[192:195], v[108:111]
	v_mfma_f32_16x16x32_bf16 v[104:107], v[160:163], v[192:195], v[104:107]
	v_mfma_f32_16x16x32_bf16 v[92:95], v[144:147], v[200:203], v[92:95]
	v_mfma_f32_16x16x32_bf16 v[88:91], v[160:163], v[200:203], v[88:91]
	v_mfma_f32_16x16x32_bf16 v[76:79], v[144:147], v[210:213], v[76:79]
	v_mfma_f32_16x16x32_bf16 v[72:75], v[160:163], v[210:213], v[72:75]
	v_mfma_f32_16x16x32_bf16 v[124:127], v[156:159], v[188:191], v[124:127]
	v_mfma_f32_16x16x32_bf16 v[120:123], v[164:167], v[188:191], v[120:123]
	v_mfma_f32_16x16x32_bf16 v[108:111], v[156:159], v[196:199], v[108:111]
	v_mfma_f32_16x16x32_bf16 v[104:107], v[164:167], v[196:199], v[104:107]
	v_mfma_f32_16x16x32_bf16 v[92:95], v[156:159], v[204:207], v[92:95]
	v_mfma_f32_16x16x32_bf16 v[88:91], v[164:167], v[204:207], v[88:91]
	v_mfma_f32_16x16x32_bf16 v[76:79], v[156:159], v[214:217], v[76:79]
	v_mfma_f32_16x16x32_bf16 v[72:75], v[164:167], v[214:217], v[72:75]
	s_setprio 0
	s_setprio 1
	v_mfma_f32_16x16x32_bf16 v[116:119], v[168:171], v[184:187], v[116:119]
	v_mfma_f32_16x16x32_bf16 v[112:115], v[176:179], v[184:187], v[112:115]
	v_mfma_f32_16x16x32_bf16 v[100:103], v[168:171], v[192:195], v[100:103]
	v_mfma_f32_16x16x32_bf16 v[96:99], v[176:179], v[192:195], v[96:99]
	v_mfma_f32_16x16x32_bf16 v[84:87], v[168:171], v[200:203], v[84:87]
	v_mfma_f32_16x16x32_bf16 v[80:83], v[176:179], v[200:203], v[80:83]
	v_mfma_f32_16x16x32_bf16 v[68:71], v[168:171], v[210:213], v[68:71]
	v_mfma_f32_16x16x32_bf16 v[64:67], v[176:179], v[210:213], v[64:67]
	v_mfma_f32_16x16x32_bf16 v[116:119], v[172:175], v[188:191], v[116:119]
	v_mfma_f32_16x16x32_bf16 v[112:115], v[180:183], v[188:191], v[112:115]
	v_mfma_f32_16x16x32_bf16 v[100:103], v[172:175], v[196:199], v[100:103]
	v_mfma_f32_16x16x32_bf16 v[96:99], v[180:183], v[196:199], v[96:99]
	v_mfma_f32_16x16x32_bf16 v[84:87], v[172:175], v[204:207], v[84:87]
	v_mfma_f32_16x16x32_bf16 v[80:83], v[180:183], v[204:207], v[80:83]
	v_mfma_f32_16x16x32_bf16 v[68:71], v[172:175], v[214:217], v[68:71]
	v_mfma_f32_16x16x32_bf16 v[64:67], v[180:183], v[214:217], v[64:67]
	s_setprio 0
	s_barrier
; #define PG8_STAGE(bufoff, gbase, voff) do { _Pragma("unroll") for (int _i = 0; _i < 2; ++_i) \
;         __builtin_amdgcn_global_load_lds((const unsigned*)((const char*)(gbase) + (voff)[_i]), (PG8_LAS unsigned*)(lds + (bufoff) + ldsw + _i * 8192), 16, 0, 0); } while (0)
; #define PG8_LDA(dst, b, h) do { _Pragma("unroll") for (int m = 0; m < 4; ++m) _Pragma("unroll") for (int k = 0; k < 2; ++k) dst[m][k] = *(const PG8_LAS bf16x8*)(lds + PG8_SA(b, h) + aoff + m * 2048 + k * 1024); } while (0)
; #define PG8_MMA(ai, bj, At, Bt) do { __builtin_amdgcn_s_setprio(1); _Pragma("unroll") for (int m = 0; m < 4; ++m) _Pragma("unroll") for (int n = 0; n < 2; ++n) _Pragma("unroll") for (int k = 0; k < 2; ++k) \
;         acc[ai][bj][m][n] = __builtin_amdgcn_mfma_f32_16x16x32_bf16(Bt[n][k], At[m][k], acc[ai][bj][m][n], 0, 0, 0); __builtin_amdgcn_s_setprio(0); } while (0)
; #define PG8_WAIT_V(n) asm volatile("s_waitcnt vmcnt(" #n ")" ::: "memory")
; #define PG8_WAIT_L(n) asm volatile("s_waitcnt lgkmcnt(" #n ")" ::: "memory")
; #define PG8_BAR __builtin_amdgcn_s_barrier()
; #define PG8_SCHED __builtin_amdgcn_sched_barrier(0)
; template <class Epi, class Sched, bool ALIGN_EPI = false, bool SP2 = false>
; __device__ __forceinline__ void gemm_phase(PG8_LAS unsigned char* lds, const Gemm g, const Sched& S, const Epi& E) {
;     ...
;         for (int t = 0; t < nt; t += 2) {
;             const bool last = (t == nt - 2);
;             const char* a1 = cA + (size_t)(t + 1) * kstep;
;             const char* a2 = last ? nA : cA + (size_t)(t + 2) * kstep; const char* b2 = last ? nB : cB + (size_t)(t + 2) * kstep;
;             const char* a3 = a2 + kstep; const char* b3 = b2 + kstep;
;     ...
;             PG8_LDA(At, 1, 1); PG8_STAGE(PG8_SB(1, 0), b3, voffB); PG8_STAGE(PG8_SB(1, 1), b3 + hstep, voffB); PG8_STAGE(PG8_SA(1, 0), a3, voffA);
;             PG8_WAIT_V(8); PG8_WAIT_L(0); PG8_BAR; PG8_MMA(1, 0, At, B0); PG8_MMA(1, 1, At, B1); PG8_BAR; PG8_SCHED;
	s_add_i32 s30, s54, s38
	v_lshl_add_u64 v[218:219], v[218:219], 0, s[10:11]
	s_mov_b32 m0, s30
	ds_read_b128 v[184:187], v153 offset:49152
	ds_read_b128 v[188:191], v153 offset:50176
	ds_read_b128 v[192:195], v153 offset:51200
	ds_read_b128 v[196:199], v153 offset:52224
	ds_read_b128 v[200:203], v153 offset:53248
	ds_read_b128 v[204:207], v153 offset:54272
	ds_read_b128 v[210:213], v153 offset:55296
	ds_read_b128 v[214:217], v153 offset:56320
	global_load_lds_dwordx4 v[218:219], off
	s_add_i32 m0, s30, 0x2000
	s_add_u32 s28, s28, 0x40080
	v_lshl_add_u64 v[218:219], v[220:221], 0, s[10:11]
	s_addc_u32 s29, s29, 0
	s_add_i32 s30, s55, s38
	global_load_lds_dwordx4 v[218:219], off
	v_lshl_add_u64 v[218:219], s[28:29], 0, v[130:131]
	s_mov_b32 m0, s30
	s_nop 0
	global_load_lds_dwordx4 v[218:219], off
	v_lshl_add_u64 v[218:219], s[28:29], 0, v[134:135]
	s_add_i32 m0, s30, 0x2000
	s_nop 0
	global_load_lds_dwordx4 v[218:219], off
	v_lshl_add_u64 v[218:219], v[222:223], 0, s[10:11]
	s_mov_b32 m0, s43
	s_nop 0
	global_load_lds_dwordx4 v[218:219], off
	v_lshl_add_u64 v[218:219], v[224:225], 0, s[10:11]
	s_mov_b32 m0, s44
	s_nop 0
	global_load_lds_dwordx4 v[218:219], off
	s_waitcnt vmcnt(8)
	s_waitcnt lgkmcnt(0)
	s_barrier
	s_setprio 1
	s_waitcnt lgkmcnt(0)
	v_mfma_f32_16x16x32_bf16 v[60:63], v[144:147], v[184:187], v[60:63]
	v_mfma_f32_16x16x32_bf16 v[56:59], v[160:163], v[184:187], v[56:59]
	v_mfma_f32_16x16x32_bf16 v[44:47], v[144:147], v[192:195], v[44:47]
	v_mfma_f32_16x16x32_bf16 v[40:43], v[160:163], v[192:195], v[40:43]
	v_mfma_f32_16x16x32_bf16 v[28:31], v[144:147], v[200:203], v[28:31]
	v_mfma_f32_16x16x32_bf16 v[24:27], v[160:163], v[200:203], v[24:27]
	v_mfma_f32_16x16x32_bf16 v[12:15], v[144:147], v[210:213], v[12:15]
	v_mfma_f32_16x16x32_bf16 v[8:11], v[160:163], v[210:213], v[8:11]
	v_mfma_f32_16x16x32_bf16 v[60:63], v[156:159], v[188:191], v[60:63]
	v_mfma_f32_16x16x32_bf16 v[56:59], v[164:167], v[188:191], v[56:59]
	v_mfma_f32_16x16x32_bf16 v[44:47], v[156:159], v[196:199], v[44:47]
	v_mfma_f32_16x16x32_bf16 v[40:43], v[164:167], v[196:199], v[40:43]
	v_mfma_f32_16x16x32_bf16 v[28:31], v[156:159], v[204:207], v[28:31]
	v_mfma_f32_16x16x32_bf16 v[24:27], v[164:167], v[204:207], v[24:27]
	v_mfma_f32_16x16x32_bf16 v[12:15], v[156:159], v[214:217], v[12:15]
	v_mfma_f32_16x16x32_bf16 v[8:11], v[164:167], v[214:217], v[8:11]
	s_setprio 0
	s_setprio 1
	v_mfma_f32_16x16x32_bf16 v[52:55], v[168:171], v[184:187], v[52:55]
	v_mfma_f32_16x16x32_bf16 v[48:51], v[176:179], v[184:187], v[48:51]
	v_mfma_f32_16x16x32_bf16 v[36:39], v[168:171], v[192:195], v[36:39]
	v_mfma_f32_16x16x32_bf16 v[32:35], v[176:179], v[192:195], v[32:35]
	v_mfma_f32_16x16x32_bf16 v[20:23], v[168:171], v[200:203], v[20:23]
	v_mfma_f32_16x16x32_bf16 v[16:19], v[176:179], v[200:203], v[16:19]
	v_mfma_f32_16x16x32_bf16 v[4:7], v[168:171], v[210:213], v[4:7]
	v_mfma_f32_16x16x32_bf16 v[0:3], v[176:179], v[210:213], v[0:3]
	v_mfma_f32_16x16x32_bf16 v[52:55], v[172:175], v[188:191], v[52:55]
	v_mfma_f32_16x16x32_bf16 v[48:51], v[180:183], v[188:191], v[48:51]
	v_mfma_f32_16x16x32_bf16 v[36:39], v[172:175], v[196:199], v[36:39]
	v_mfma_f32_16x16x32_bf16 v[32:35], v[180:183], v[196:199], v[32:35]
	v_mfma_f32_16x16x32_bf16 v[20:23], v[172:175], v[204:207], v[20:23]
	v_mfma_f32_16x16x32_bf16 v[16:19], v[180:183], v[204:207], v[16:19]
	v_mfma_f32_16x16x32_bf16 v[4:7], v[172:175], v[214:217], v[4:7]
	v_mfma_f32_16x16x32_bf16 v[0:3], v[180:183], v[214:217], v[0:3]
	s_setprio 0
	s_add_i32 s53, s53, 2
	s_add_u32 s26, s26, 0x100
	s_addc_u32 s27, s27, 0
	s_add_u32 s51, s51, 0x100
	s_addc_u32 s52, s52, 0
	s_cmp_gt_u32 s53, 13
	s_barrier
	s_cbranch_scc0 .LBB0_1013
	s_and_b64 vcc, exec, s[12:13]
	s_cbranch_vccz .LBB0_1016
	s_barrier

; #define PG8_STAGE(bufoff, gbase, voff) do { _Pragma("unroll") for (int _i = 0; _i < 2; ++_i) \
;         __builtin_amdgcn_global_load_lds((const unsigned*)((const char*)(gbase) + (voff)[_i]), (PG8_LAS unsigned*)(lds + (bufoff) + ldsw + _i * 8192), 16, 0, 0); } while (0)
; #define PG8_LDA(dst, b, h) do { _Pragma("unroll") for (int m = 0; m < 4; ++m) _Pragma("unroll") for (int k = 0; k < 2; ++k) dst[m][k] = *(const PG8_LAS bf16x8*)(lds + PG8_SA(b, h) + aoff + m * 2048 + k * 1024); } while (0)
; #define PG8_LDB(dst, b, h) do { _Pragma("unroll") for (int n = 0; n < 2; ++n) _Pragma("unroll") for (int k = 0; k < 2; ++k) dst[n][k] = *(const PG8_LAS bf16x8*)(lds + PG8_SB(b, h) + boff + n * 2048 + k * 1024); } while (0)
; #define PG8_MMA(ai, bj, At, Bt) do { __builtin_amdgcn_s_setprio(1); _Pragma("unroll") for (int m = 0; m < 4; ++m) _Pragma("unroll") for (int n = 0; n < 2; ++n) _Pragma("unroll") for (int k = 0; k < 2; ++k) \
;         acc[ai][bj][m][n] = __builtin_amdgcn_mfma_f32_16x16x32_bf16(Bt[n][k], At[m][k], acc[ai][bj][m][n], 0, 0, 0); __builtin_amdgcn_s_setprio(0); } while (0)
; #define PG8_WAIT_V(n) asm volatile("s_waitcnt vmcnt(" #n ")" ::: "memory")
; #define PG8_BAR __builtin_amdgcn_s_barrier()
; template <class Epi, class Sched, bool ALIGN_EPI = false, bool SP2 = false>
; __device__ __forceinline__ void gemm_phase(PG8_LAS unsigned char* lds, const Gemm g, const Sched& S, const Epi& E) {
;     ...
;         for (int t = 0; t < nt; t += 2) {
;             const bool last = (t == nt - 2);
;             const char* a1 = cA + (size_t)(t + 1) * kstep;
;             const char* a2 = last ? nA : cA + (size_t)(t + 2) * kstep; const char* b2 = last ? nB : cB + (size_t)(t + 2) * kstep;
;             const char* a3 = a2 + kstep; const char* b3 = b2 + kstep;
;             if (last && has_next) S.a_ready(nxt);
;             if constexpr (SP2) {
;             PG8_LDB(B0, 0, 0); PG8_LDB(B1, 0, 1); PG8_SCHED; PG8_LDA(At, 0, 0); PG8_STAGE(PG8_SA(1, 1), a1 + hstep, voffA);
;             PG8_WAIT_V(8); PG8_WAIT_L(0); PG8_BAR; PG8_MMA(0, 0, At, B0); PG8_MMA(0, 1, At, B1); PG8_BAR; PG8_SCHED;
;             PG8_LDA(At, 0, 1); PG8_STAGE(PG8_SB(0, 0), b2, voffB); PG8_STAGE(PG8_SB(0, 1), b2 + hstep, voffB); PG8_STAGE(PG8_SA(0, 0), a2, voffA);
;             PG8_WAIT_V(8); PG8_WAIT_L(0); PG8_BAR; PG8_MMA(1, 0, At, B0); PG8_MMA(1, 1, At, B1); PG8_BAR; PG8_SCHED;
.LBB0_1103:
	ds_read_b128 v[144:147], v155
	ds_read_b128 v[148:151], v155 offset:1024
	ds_read_b128 v[160:163], v155 offset:2048
	ds_read_b128 v[164:167], v155 offset:3072
	ds_read_b128 v[168:171], v156
	ds_read_b128 v[172:175], v156 offset:1024
	ds_read_b128 v[176:179], v156 offset:2048
	ds_read_b128 v[180:183], v156 offset:3072
	s_add_u32 s24, s22, 0xfffc0080
	s_addc_u32 s25, s23, -1
	s_cmp_eq_u32 s53, 12
	s_cselect_b32 s27, s15, s25
	s_cselect_b32 s26, s49, s24
	s_cselect_b32 s25, s13, s52
	s_cselect_b32 s24, s50, s51
	v_lshl_add_u64 v[218:219], s[22:23], 0, v[136:137]
	s_add_i32 m0, s21, 0xc000
	ds_read_b128 v[184:187], v157
	ds_read_b128 v[188:191], v157 offset:1024
	ds_read_b128 v[192:195], v157 offset:2048
	ds_read_b128 v[196:199], v157 offset:3072
	ds_read_b128 v[200:203], v157 offset:4096
	ds_read_b128 v[204:207], v157 offset:5120
	ds_read_b128 v[210:213], v157 offset:6144
	ds_read_b128 v[214:217], v157 offset:7168
	global_load_lds_dwordx4 v[218:219], off
	v_lshl_add_u64 v[218:219], s[22:23], 0, v[138:139]
	s_add_i32 m0, s21, 0xe000
	s_nop 0
	global_load_lds_dwordx4 v[218:219], off
	s_waitcnt vmcnt(8)
	s_waitcnt lgkmcnt(0)
	s_barrier
	s_setprio 1
	s_waitcnt lgkmcnt(0)
	v_mfma_f32_16x16x32_bf16 v[124:127], v[144:147], v[184:187], v[124:127]
	v_mfma_f32_16x16x32_bf16 v[120:123], v[160:163], v[184:187], v[120:123]
	v_mfma_f32_16x16x32_bf16 v[108:111], v[144:147], v[192:195], v[108:111]
	v_mfma_f32_16x16x32_bf16 v[104:107], v[160:163], v[192:195], v[104:107]
	v_mfma_f32_16x16x32_bf16 v[92:95], v[144:147], v[200:203], v[92:95]
	v_mfma_f32_16x16x32_bf16 v[88:91], v[160:163], v[200:203], v[88:91]
	v_mfma_f32_16x16x32_bf16 v[76:79], v[144:147], v[210:213], v[76:79]
	v_mfma_f32_16x16x32_bf16 v[72:75], v[160:163], v[210:213], v[72:75]
	v_mfma_f32_16x16x32_bf16 v[124:127], v[148:151], v[188:191], v[124:127]
	v_mfma_f32_16x16x32_bf16 v[120:123], v[164:167], v[188:191], v[120:123]
	v_mfma_f32_16x16x32_bf16 v[108:111], v[148:151], v[196:199], v[108:111]
	v_mfma_f32_16x16x32_bf16 v[104:107], v[164:167], v[196:199], v[104:107]
	v_mfma_f32_16x16x32_bf16 v[92:95], v[148:151], v[204:207], v[92:95]
	v_mfma_f32_16x16x32_bf16 v[88:91], v[164:167], v[204:207], v[88:91]
	v_mfma_f32_16x16x32_bf16 v[76:79], v[148:151], v[214:217], v[76:79]
	v_mfma_f32_16x16x32_bf16 v[72:75], v[164:167], v[214:217], v[72:75]
	s_setprio 0
	s_setprio 1
	v_mfma_f32_16x16x32_bf16 v[116:119], v[168:171], v[184:187], v[116:119]
	v_mfma_f32_16x16x32_bf16 v[112:115], v[176:179], v[184:187], v[112:115]
	v_mfma_f32_16x16x32_bf16 v[100:103], v[168:171], v[192:195], v[100:103]
	v_mfma_f32_16x16x32_bf16 v[96:99], v[176:179], v[192:195], v[96:99]
	v_mfma_f32_16x16x32_bf16 v[84:87], v[168:171], v[200:203], v[84:87]
	v_mfma_f32_16x16x32_bf16 v[80:83], v[176:179], v[200:203], v[80:83]
	v_mfma_f32_16x16x32_bf16 v[68:71], v[168:171], v[210:213], v[68:71]
	v_mfma_f32_16x16x32_bf16 v[64:67], v[176:179], v[210:213], v[64:67]
	v_mfma_f32_16x16x32_bf16 v[116:119], v[172:175], v[188:191], v[116:119]
	v_mfma_f32_16x16x32_bf16 v[112:115], v[180:183], v[188:191], v[112:115]
	v_mfma_f32_16x16x32_bf16 v[100:103], v[172:175], v[196:199], v[100:103]
	v_mfma_f32_16x16x32_bf16 v[96:99], v[180:183], v[196:199], v[96:99]
	v_mfma_f32_16x16x32_bf16 v[84:87], v[172:175], v[204:207], v[84:87]
	v_mfma_f32_16x16x32_bf16 v[80:83], v[180:183], v[204:207], v[80:83]
	v_mfma_f32_16x16x32_bf16 v[68:71], v[172:175], v[214:217], v[68:71]
	v_mfma_f32_16x16x32_bf16 v[64:67], v[180:183], v[214:217], v[64:67]
	s_setprio 0
	s_barrier
	s_add_i32 s54, s45, s34
	v_lshl_add_u64 v[218:219], s[24:25], 0, v[130:131]
	s_mov_b32 m0, s54
	ds_read_b128 v[184:187], v157 offset:16384
	ds_read_b128 v[188:191], v157 offset:17408
	ds_read_b128 v[192:195], v157 offset:18432
	ds_read_b128 v[196:199], v157 offset:19456
	ds_read_b128 v[200:203], v157 offset:20480
	ds_read_b128 v[204:207], v157 offset:21504
	ds_read_b128 v[210:213], v157 offset:22528
	ds_read_b128 v[214:217], v157 offset:23552
	global_load_lds_dwordx4 v[218:219], off
	s_add_i32 m0, s54, 0x2000
	s_add_u32 s54, s24, 0x40000
	v_lshl_add_u64 v[220:221], s[24:25], 0, v[134:135]
	s_addc_u32 s55, s25, 0
	s_add_i32 s56, s46, s34
	global_load_lds_dwordx4 v[220:221], off
	v_lshl_add_u64 v[222:223], s[54:55], 0, v[130:131]
	s_mov_b32 m0, s56
	v_lshl_add_u64 v[224:225], s[26:27], 0, v[132:133]
	global_load_lds_dwordx4 v[222:223], off
	v_lshl_add_u64 v[222:223], s[54:55], 0, v[134:135]
	s_add_i32 m0, s56, 0x2000
	s_nop 0
	global_load_lds_dwordx4 v[222:223], off
	v_lshl_add_u64 v[222:223], s[26:27], 0, v[128:129]
	s_mov_b32 m0, s21
	s_nop 0
	global_load_lds_dwordx4 v[222:223], off
	s_mov_b32 m0, s37
	s_nop 0
	global_load_lds_dwordx4 v[224:225], off
	s_waitcnt vmcnt(8)
	s_waitcnt lgkmcnt(0)
	s_barrier
; #define PG8_STAGE(bufoff, gbase, voff) do { _Pragma("unroll") for (int _i = 0; _i < 2; ++_i) \
;         __builtin_amdgcn_global_load_lds((const unsigned*)((const char*)(gbase) + (voff)[_i]), (PG8_LAS unsigned*)(lds + (bufoff) + ldsw + _i * 8192), 16, 0, 0); } while (0)
; #define PG8_LDA(dst, b, h) do { _Pragma("unroll") for (int m = 0; m < 4; ++m) _Pragma("unroll") for (int k = 0; k < 2; ++k) dst[m][k] = *(const PG8_LAS bf16x8*)(lds + PG8_SA(b, h) + aoff + m * 2048 + k * 1024); } while (0)
; #define PG8_LDB(dst, b, h) do { _Pragma("unroll") for (int n = 0; n < 2; ++n) _Pragma("unroll") for (int k = 0; k < 2; ++k) dst[n][k] = *(const PG8_LAS bf16x8*)(lds + PG8_SB(b, h) + boff + n * 2048 + k * 1024); } while (0)
; #define PG8_MMA(ai, bj, At, Bt) do { __builtin_amdgcn_s_setprio(1); _Pragma("unroll") for (int m = 0; m < 4; ++m) _Pragma("unroll") for (int n = 0; n < 2; ++n) _Pragma("unroll") for (int k = 0; k < 2; ++k) \
;         acc[ai][bj][m][n] = __builtin_amdgcn_mfma_f32_16x16x32_bf16(Bt[n][k], At[m][k], acc[ai][bj][m][n], 0, 0, 0); __builtin_amdgcn_s_setprio(0); } while (0)
; #define PG8_WAIT_V(n) asm volatile("s_waitcnt vmcnt(" #n ")" ::: "memory")
; #define PG8_WAIT_L(n) asm volatile("s_waitcnt lgkmcnt(" #n ")" ::: "memory")
; #define PG8_BAR __builtin_amdgcn_s_barrier()
; #define PG8_SCHED __builtin_amdgcn_sched_barrier(0)
; template <class Epi, class Sched, bool ALIGN_EPI = false, bool SP2 = false>
; __device__ __forceinline__ void gemm_phase(PG8_LAS unsigned char* lds, const Gemm g, const Sched& S, const Epi& E) {
;     ...
;             PG8_WAIT_V(8); PG8_WAIT_L(0); PG8_BAR; PG8_MMA(1, 0, At, B0); PG8_MMA(1, 1, At, B1); PG8_BAR; PG8_SCHED;
;             PG8_LDB(B0, 1, 0); PG8_LDB(B1, 1, 1); PG8_SCHED; PG8_LDA(At, 1, 0); PG8_STAGE(PG8_SA(0, 1), a2 + hstep, voffA);
;             PG8_WAIT_V(8); PG8_WAIT_L(0); PG8_BAR; PG8_MMA(0, 0, At, B0); PG8_MMA(0, 1, At, B1); PG8_BAR; PG8_SCHED;
	s_setprio 1
	s_waitcnt lgkmcnt(0)
	v_mfma_f32_16x16x32_bf16 v[60:63], v[144:147], v[184:187], v[60:63]
	v_mfma_f32_16x16x32_bf16 v[56:59], v[160:163], v[184:187], v[56:59]
	v_mfma_f32_16x16x32_bf16 v[44:47], v[144:147], v[192:195], v[44:47]
	v_mfma_f32_16x16x32_bf16 v[40:43], v[160:163], v[192:195], v[40:43]
	v_mfma_f32_16x16x32_bf16 v[28:31], v[144:147], v[200:203], v[28:31]
	v_mfma_f32_16x16x32_bf16 v[24:27], v[160:163], v[200:203], v[24:27]
	v_mfma_f32_16x16x32_bf16 v[12:15], v[144:147], v[210:213], v[12:15]
	v_mfma_f32_16x16x32_bf16 v[8:11], v[160:163], v[210:213], v[8:11]
	v_mfma_f32_16x16x32_bf16 v[60:63], v[148:151], v[188:191], v[60:63]
	v_mfma_f32_16x16x32_bf16 v[56:59], v[164:167], v[188:191], v[56:59]
	v_mfma_f32_16x16x32_bf16 v[44:47], v[148:151], v[196:199], v[44:47]
	v_mfma_f32_16x16x32_bf16 v[40:43], v[164:167], v[196:199], v[40:43]
	v_mfma_f32_16x16x32_bf16 v[28:31], v[148:151], v[204:207], v[28:31]
	v_mfma_f32_16x16x32_bf16 v[24:27], v[164:167], v[204:207], v[24:27]
	v_mfma_f32_16x16x32_bf16 v[12:15], v[148:151], v[214:217], v[12:15]
	v_mfma_f32_16x16x32_bf16 v[8:11], v[164:167], v[214:217], v[8:11]
	s_setprio 0
	s_setprio 1
	v_mfma_f32_16x16x32_bf16 v[52:55], v[168:171], v[184:187], v[52:55]
	v_mfma_f32_16x16x32_bf16 v[48:51], v[176:179], v[184:187], v[48:51]
	v_mfma_f32_16x16x32_bf16 v[36:39], v[168:171], v[192:195], v[36:39]
	v_mfma_f32_16x16x32_bf16 v[32:35], v[176:179], v[192:195], v[32:35]
	v_mfma_f32_16x16x32_bf16 v[20:23], v[168:171], v[200:203], v[20:23]
	v_mfma_f32_16x16x32_bf16 v[16:19], v[176:179], v[200:203], v[16:19]
	v_mfma_f32_16x16x32_bf16 v[4:7], v[168:171], v[210:213], v[4:7]
	v_mfma_f32_16x16x32_bf16 v[0:3], v[176:179], v[210:213], v[0:3]
	v_mfma_f32_16x16x32_bf16 v[52:55], v[172:175], v[188:191], v[52:55]
	v_mfma_f32_16x16x32_bf16 v[48:51], v[180:183], v[188:191], v[48:51]
	v_mfma_f32_16x16x32_bf16 v[36:39], v[172:175], v[196:199], v[36:39]
	v_mfma_f32_16x16x32_bf16 v[32:35], v[180:183], v[196:199], v[32:35]
	v_mfma_f32_16x16x32_bf16 v[20:23], v[172:175], v[204:207], v[20:23]
	v_mfma_f32_16x16x32_bf16 v[16:19], v[180:183], v[204:207], v[16:19]
	v_mfma_f32_16x16x32_bf16 v[4:7], v[172:175], v[214:217], v[4:7]
	v_mfma_f32_16x16x32_bf16 v[0:3], v[180:183], v[214:217], v[0:3]
	s_setprio 0
	s_barrier
	s_add_i32 s54, 0, 0x18000
	v_add_u32_e32 v159, s54, v153
	s_add_i32 s55, 0, 0x1c000
	ds_read_b128 v[144:147], v159
	ds_read_b128 v[148:151], v159 offset:1024
	ds_read_b128 v[160:163], v159 offset:2048
	ds_read_b128 v[164:167], v159 offset:3072
	v_add_u32_e32 v159, s55, v153
	ds_read_b128 v[168:171], v159
	ds_read_b128 v[172:175], v159 offset:1024
	ds_read_b128 v[176:179], v159 offset:2048
	ds_read_b128 v[180:183], v159 offset:3072
	s_add_u32 s26, s26, 0x40000
	s_addc_u32 s27, s27, 0
	s_mov_b32 m0, s38
	v_lshl_add_u64 v[226:227], s[26:27], 0, v[128:129]
	ds_read_b128 v[184:187], v157 offset:32768
	ds_read_b128 v[188:191], v157 offset:33792
	ds_read_b128 v[192:195], v157 offset:34816
	ds_read_b128 v[196:199], v157 offset:35840
	ds_read_b128 v[200:203], v157 offset:36864
	ds_read_b128 v[204:207], v157 offset:37888
	ds_read_b128 v[210:213], v157 offset:38912
	ds_read_b128 v[214:217], v157 offset:39936
	global_load_lds_dwordx4 v[226:227], off
	v_lshl_add_u64 v[226:227], s[26:27], 0, v[132:133]
	s_mov_b32 m0, s39
	s_nop 0
	global_load_lds_dwordx4 v[226:227], off
	s_waitcnt vmcnt(8)
	s_waitcnt lgkmcnt(0)
	s_barrier
	s_setprio 1
	s_waitcnt lgkmcnt(0)
	v_mfma_f32_16x16x32_bf16 v[124:127], v[144:147], v[184:187], v[124:127]
	v_mfma_f32_16x16x32_bf16 v[120:123], v[160:163], v[184:187], v[120:123]
	v_mfma_f32_16x16x32_bf16 v[108:111], v[144:147], v[192:195], v[108:111]
	v_mfma_f32_16x16x32_bf16 v[104:107], v[160:163], v[192:195], v[104:107]
	v_mfma_f32_16x16x32_bf16 v[92:95], v[144:147], v[200:203], v[92:95]
	v_mfma_f32_16x16x32_bf16 v[88:91], v[160:163], v[200:203], v[88:91]
	v_mfma_f32_16x16x32_bf16 v[76:79], v[144:147], v[210:213], v[76:79]
	v_mfma_f32_16x16x32_bf16 v[72:75], v[160:163], v[210:213], v[72:75]
	v_mfma_f32_16x16x32_bf16 v[124:127], v[148:151], v[188:191], v[124:127]
	v_mfma_f32_16x16x32_bf16 v[120:123], v[164:167], v[188:191], v[120:123]
	v_mfma_f32_16x16x32_bf16 v[108:111], v[148:151], v[196:199], v[108:111]
	v_mfma_f32_16x16x32_bf16 v[104:107], v[164:167], v[196:199], v[104:107]
	v_mfma_f32_16x16x32_bf16 v[92:95], v[148:151], v[204:207], v[92:95]
	v_mfma_f32_16x16x32_bf16 v[88:91], v[164:167], v[204:207], v[88:91]
	v_mfma_f32_16x16x32_bf16 v[76:79], v[148:151], v[214:217], v[76:79]
	v_mfma_f32_16x16x32_bf16 v[72:75], v[164:167], v[214:217], v[72:75]
	s_setprio 0
	s_setprio 1
	v_mfma_f32_16x16x32_bf16 v[116:119], v[168:171], v[184:187], v[116:119]
	v_mfma_f32_16x16x32_bf16 v[112:115], v[176:179], v[184:187], v[112:115]
	v_mfma_f32_16x16x32_bf16 v[100:103], v[168:171], v[192:195], v[100:103]
	v_mfma_f32_16x16x32_bf16 v[96:99], v[176:179], v[192:195], v[96:99]
	v_mfma_f32_16x16x32_bf16 v[84:87], v[168:171], v[200:203], v[84:87]
	v_mfma_f32_16x16x32_bf16 v[80:83], v[176:179], v[200:203], v[80:83]
	v_mfma_f32_16x16x32_bf16 v[68:71], v[168:171], v[210:213], v[68:71]
	v_mfma_f32_16x16x32_bf16 v[64:67], v[176:179], v[210:213], v[64:67]
	v_mfma_f32_16x16x32_bf16 v[116:119], v[172:175], v[188:191], v[116:119]
	v_mfma_f32_16x16x32_bf16 v[112:115], v[180:183], v[188:191], v[112:115]
	v_mfma_f32_16x16x32_bf16 v[100:103], v[172:175], v[196:199], v[100:103]
	v_mfma_f32_16x16x32_bf16 v[96:99], v[180:183], v[196:199], v[96:99]
	v_mfma_f32_16x16x32_bf16 v[84:87], v[172:175], v[204:207], v[84:87]
	v_mfma_f32_16x16x32_bf16 v[80:83], v[180:183], v[204:207], v[80:83]
	v_mfma_f32_16x16x32_bf16 v[68:71], v[172:175], v[214:217], v[68:71]
	v_mfma_f32_16x16x32_bf16 v[64:67], v[180:183], v[214:217], v[64:67]
	s_setprio 0
	s_barrier
; #define PG8_STAGE(bufoff, gbase, voff) do { _Pragma("unroll") for (int _i = 0; _i < 2; ++_i) \
;         __builtin_amdgcn_global_load_lds((const unsigned*)((const char*)(gbase) + (voff)[_i]), (PG8_LAS unsigned*)(lds + (bufoff) + ldsw + _i * 8192), 16, 0, 0); } while (0)
; #define PG8_LDA(dst, b, h) do { _Pragma("unroll") for (int m = 0; m < 4; ++m) _Pragma("unroll") for (int k = 0; k < 2; ++k) dst[m][k] = *(const PG8_LAS bf16x8*)(lds + PG8_SA(b, h) + aoff + m * 2048 + k * 1024); } while (0)
; #define PG8_MMA(ai, bj, At, Bt) do { __builtin_amdgcn_s_setprio(1); _Pragma("unroll") for (int m = 0; m < 4; ++m) _Pragma("unroll") for (int n = 0; n < 2; ++n) _Pragma("unroll") for (int k = 0; k < 2; ++k) \
;         acc[ai][bj][m][n] = __builtin_amdgcn_mfma_f32_16x16x32_bf16(Bt[n][k], At[m][k], acc[ai][bj][m][n], 0, 0, 0); __builtin_amdgcn_s_setprio(0); } while (0)
; #define PG8_WAIT_V(n) asm volatile("s_waitcnt vmcnt(" #n ")" ::: "memory")
; #define PG8_WAIT_L(n) asm volatile("s_waitcnt lgkmcnt(" #n ")" ::: "memory")
; #define PG8_BAR __builtin_amdgcn_s_barrier()
; #define PG8_SCHED __builtin_amdgcn_sched_barrier(0)
; template <class Epi, class Sched, bool ALIGN_EPI = false, bool SP2 = false>
; __device__ __forceinline__ void gemm_phase(PG8_LAS unsigned char* lds, const Gemm g, const Sched& S, const Epi& E) {
;     ...
;         for (int t = 0; t < nt; t += 2) {
;             const bool last = (t == nt - 2);
;             const char* a1 = cA + (size_t)(t + 1) * kstep;
;             const char* a2 = last ? nA : cA + (size_t)(t + 2) * kstep; const char* b2 = last ? nB : cB + (size_t)(t + 2) * kstep;
;             const char* a3 = a2 + kstep; const char* b3 = b2 + kstep;
;     ...
;             PG8_LDA(At, 1, 1); PG8_STAGE(PG8_SB(1, 0), b3, voffB); PG8_STAGE(PG8_SB(1, 1), b3 + hstep, voffB); PG8_STAGE(PG8_SA(1, 0), a3, voffA);
;             PG8_WAIT_V(8); PG8_WAIT_L(0); PG8_BAR; PG8_MMA(1, 0, At, B0); PG8_MMA(1, 1, At, B1); PG8_BAR; PG8_SCHED;
	s_add_i32 s26, s54, s34
	v_lshl_add_u64 v[218:219], v[218:219], 0, s[8:9]
	s_mov_b32 m0, s26
	ds_read_b128 v[184:187], v157 offset:49152
	ds_read_b128 v[188:191], v157 offset:50176
	ds_read_b128 v[192:195], v157 offset:51200
	ds_read_b128 v[196:199], v157 offset:52224
	ds_read_b128 v[200:203], v157 offset:53248
	ds_read_b128 v[204:207], v157 offset:54272
	ds_read_b128 v[210:213], v157 offset:55296
	ds_read_b128 v[214:217], v157 offset:56320
	global_load_lds_dwordx4 v[218:219], off
	s_add_i32 m0, s26, 0x2000
	s_add_u32 s24, s24, 0x40080
	v_lshl_add_u64 v[218:219], v[220:221], 0, s[8:9]
	s_addc_u32 s25, s25, 0
	s_add_i32 s26, s55, s34
	global_load_lds_dwordx4 v[218:219], off
	v_lshl_add_u64 v[218:219], s[24:25], 0, v[130:131]
	s_mov_b32 m0, s26
	s_nop 0
	global_load_lds_dwordx4 v[218:219], off
	v_lshl_add_u64 v[218:219], s[24:25], 0, v[134:135]
	s_add_i32 m0, s26, 0x2000
	s_nop 0
	global_load_lds_dwordx4 v[218:219], off
	v_lshl_add_u64 v[218:219], v[222:223], 0, s[8:9]
	s_mov_b32 m0, s42
	s_nop 0
	global_load_lds_dwordx4 v[218:219], off
	v_lshl_add_u64 v[218:219], v[224:225], 0, s[8:9]
	s_mov_b32 m0, s43
	s_nop 0
	global_load_lds_dwordx4 v[218:219], off
	s_waitcnt vmcnt(8)
	s_waitcnt lgkmcnt(0)
	s_barrier
	s_setprio 1
	s_waitcnt lgkmcnt(0)
	v_mfma_f32_16x16x32_bf16 v[60:63], v[144:147], v[184:187], v[60:63]
	v_mfma_f32_16x16x32_bf16 v[56:59], v[160:163], v[184:187], v[56:59]
	v_mfma_f32_16x16x32_bf16 v[44:47], v[144:147], v[192:195], v[44:47]
	v_mfma_f32_16x16x32_bf16 v[40:43], v[160:163], v[192:195], v[40:43]
	v_mfma_f32_16x16x32_bf16 v[28:31], v[144:147], v[200:203], v[28:31]
	v_mfma_f32_16x16x32_bf16 v[24:27], v[160:163], v[200:203], v[24:27]
	v_mfma_f32_16x16x32_bf16 v[12:15], v[144:147], v[210:213], v[12:15]
	v_mfma_f32_16x16x32_bf16 v[8:11], v[160:163], v[210:213], v[8:11]
	v_mfma_f32_16x16x32_bf16 v[60:63], v[148:151], v[188:191], v[60:63]
	v_mfma_f32_16x16x32_bf16 v[56:59], v[164:167], v[188:191], v[56:59]
	v_mfma_f32_16x16x32_bf16 v[44:47], v[148:151], v[196:199], v[44:47]
	v_mfma_f32_16x16x32_bf16 v[40:43], v[164:167], v[196:199], v[40:43]
	v_mfma_f32_16x16x32_bf16 v[28:31], v[148:151], v[204:207], v[28:31]
	v_mfma_f32_16x16x32_bf16 v[24:27], v[164:167], v[204:207], v[24:27]
	v_mfma_f32_16x16x32_bf16 v[12:15], v[148:151], v[214:217], v[12:15]
	v_mfma_f32_16x16x32_bf16 v[8:11], v[164:167], v[214:217], v[8:11]
	s_setprio 0
	s_setprio 1
	v_mfma_f32_16x16x32_bf16 v[52:55], v[168:171], v[184:187], v[52:55]
	v_mfma_f32_16x16x32_bf16 v[48:51], v[176:179], v[184:187], v[48:51]
	v_mfma_f32_16x16x32_bf16 v[36:39], v[168:171], v[192:195], v[36:39]
	v_mfma_f32_16x16x32_bf16 v[32:35], v[176:179], v[192:195], v[32:35]
	v_mfma_f32_16x16x32_bf16 v[20:23], v[168:171], v[200:203], v[20:23]
	v_mfma_f32_16x16x32_bf16 v[16:19], v[176:179], v[200:203], v[16:19]
	v_mfma_f32_16x16x32_bf16 v[4:7], v[168:171], v[210:213], v[4:7]
	v_mfma_f32_16x16x32_bf16 v[0:3], v[176:179], v[210:213], v[0:3]
	v_mfma_f32_16x16x32_bf16 v[52:55], v[172:175], v[188:191], v[52:55]
	v_mfma_f32_16x16x32_bf16 v[48:51], v[180:183], v[188:191], v[48:51]
	v_mfma_f32_16x16x32_bf16 v[36:39], v[172:175], v[196:199], v[36:39]
	v_mfma_f32_16x16x32_bf16 v[32:35], v[180:183], v[196:199], v[32:35]
	v_mfma_f32_16x16x32_bf16 v[20:23], v[172:175], v[204:207], v[20:23]
	v_mfma_f32_16x16x32_bf16 v[16:19], v[180:183], v[204:207], v[16:19]
	v_mfma_f32_16x16x32_bf16 v[4:7], v[172:175], v[214:217], v[4:7]
	v_mfma_f32_16x16x32_bf16 v[0:3], v[180:183], v[214:217], v[0:3]
	s_setprio 0
	s_add_i32 s53, s53, 2
	s_add_u32 s22, s22, 0x100
	s_addc_u32 s23, s23, 0
	s_add_u32 s51, s51, 0x100
	s_addc_u32 s52, s52, 0
	s_cmp_gt_u32 s53, 13
	s_barrier
	s_cbranch_scc0 .LBB0_1103
	s_and_b64 vcc, exec, s[10:11]
	s_cbranch_vccz .LBB0_1106
	s_barrier

; #define PG8_STAGE(bufoff, gbase, voff) do { _Pragma("unroll") for (int _i = 0; _i < 2; ++_i) \
;         __builtin_amdgcn_global_load_lds((const unsigned*)((const char*)(gbase) + (voff)[_i]), (PG8_LAS unsigned*)(lds + (bufoff) + ldsw + _i * 8192), 16, 0, 0); } while (0)
; #define PG8_LDA(dst, b, h) do { _Pragma("unroll") for (int m = 0; m < 4; ++m) _Pragma("unroll") for (int k = 0; k < 2; ++k) dst[m][k] = *(const PG8_LAS bf16x8*)(lds + PG8_SA(b, h) + aoff + m * 2048 + k * 1024); } while (0)
; #define PG8_MMA(ai, bj, At, Bt) do { __builtin_amdgcn_s_setprio(1); _Pragma("unroll") for (int m = 0; m < 4; ++m) _Pragma("unroll") for (int n = 0; n < 2; ++n) _Pragma("unroll") for (int k = 0; k < 2; ++k) \
;         acc[ai][bj][m][n] = __builtin_amdgcn_mfma_f32_16x16x32_bf16(Bt[n][k], At[m][k], acc[ai][bj][m][n], 0, 0, 0); __builtin_amdgcn_s_setprio(0); } while (0)
; #define PG8_WAIT_V(n) asm volatile("s_waitcnt vmcnt(" #n ")" ::: "memory")
; #define PG8_WAIT_L(n) asm volatile("s_waitcnt lgkmcnt(" #n ")" ::: "memory")
; #define PG8_BAR __builtin_amdgcn_s_barrier()
; #define PG8_SCHED __builtin_amdgcn_sched_barrier(0)
; template <class Epi, class Sched, bool ALIGN_EPI = false, bool SP2 = false>
; __device__ __forceinline__ void gemm_phase(PG8_LAS unsigned char* lds, const Gemm g, const Sched& S, const Epi& E) {
;     ...
;             PG8_WAIT_V(8); PG8_WAIT_L(0); PG8_BAR; PG8_MMA(0, 0, At, B0); PG8_MMA(0, 1, At, B1); PG8_BAR; PG8_SCHED;
;             PG8_LDA(At, 0, 1); PG8_STAGE(PG8_SB(0, 0), b2, voffB); PG8_STAGE(PG8_SB(0, 1), b2 + hstep, voffB); PG8_STAGE(PG8_SA(0, 0), a2, voffA);
;             PG8_WAIT_V(8); PG8_WAIT_L(0); PG8_BAR; PG8_MMA(1, 0, At, B0); PG8_MMA(1, 1, At, B1); PG8_BAR; PG8_SCHED;
.Lmy_pf13_skip:
	s_setprio 1
	s_waitcnt lgkmcnt(0)
	v_mfma_f32_16x16x32_bf16 v[124:127], v[144:147], v[182:185], v[124:127]
	v_mfma_f32_16x16x32_bf16 v[120:123], v[158:161], v[182:185], v[120:123]
	v_mfma_f32_16x16x32_bf16 v[108:111], v[144:147], v[190:193], v[108:111]
	v_mfma_f32_16x16x32_bf16 v[104:107], v[158:161], v[190:193], v[104:107]
	v_mfma_f32_16x16x32_bf16 v[92:95], v[144:147], v[198:201], v[92:95]
	v_mfma_f32_16x16x32_bf16 v[88:91], v[158:161], v[198:201], v[88:91]
	v_mfma_f32_16x16x32_bf16 v[76:79], v[144:147], v[206:209], v[76:79]
	v_mfma_f32_16x16x32_bf16 v[72:75], v[158:161], v[206:209], v[72:75]
	v_mfma_f32_16x16x32_bf16 v[124:127], v[154:157], v[186:189], v[124:127]
	v_mfma_f32_16x16x32_bf16 v[120:123], v[162:165], v[186:189], v[120:123]
	v_mfma_f32_16x16x32_bf16 v[108:111], v[154:157], v[194:197], v[108:111]
	v_mfma_f32_16x16x32_bf16 v[104:107], v[162:165], v[194:197], v[104:107]
	v_mfma_f32_16x16x32_bf16 v[92:95], v[154:157], v[202:205], v[92:95]
	v_mfma_f32_16x16x32_bf16 v[88:91], v[162:165], v[202:205], v[88:91]
	v_mfma_f32_16x16x32_bf16 v[76:79], v[154:157], v[210:213], v[76:79]
	v_mfma_f32_16x16x32_bf16 v[72:75], v[162:165], v[210:213], v[72:75]
	s_setprio 0
	s_setprio 1
	v_mfma_f32_16x16x32_bf16 v[116:119], v[166:169], v[182:185], v[116:119]
	v_mfma_f32_16x16x32_bf16 v[112:115], v[174:177], v[182:185], v[112:115]
	v_mfma_f32_16x16x32_bf16 v[100:103], v[166:169], v[190:193], v[100:103]
	v_mfma_f32_16x16x32_bf16 v[96:99], v[174:177], v[190:193], v[96:99]
	v_mfma_f32_16x16x32_bf16 v[84:87], v[166:169], v[198:201], v[84:87]
	v_mfma_f32_16x16x32_bf16 v[80:83], v[174:177], v[198:201], v[80:83]
	v_mfma_f32_16x16x32_bf16 v[68:71], v[166:169], v[206:209], v[68:71]
	v_mfma_f32_16x16x32_bf16 v[64:67], v[174:177], v[206:209], v[64:67]
	v_mfma_f32_16x16x32_bf16 v[116:119], v[170:173], v[186:189], v[116:119]
	v_mfma_f32_16x16x32_bf16 v[112:115], v[178:181], v[186:189], v[112:115]
	v_mfma_f32_16x16x32_bf16 v[100:103], v[170:173], v[194:197], v[100:103]
	v_mfma_f32_16x16x32_bf16 v[96:99], v[178:181], v[194:197], v[96:99]
	v_mfma_f32_16x16x32_bf16 v[84:87], v[170:173], v[202:205], v[84:87]
	v_mfma_f32_16x16x32_bf16 v[80:83], v[178:181], v[202:205], v[80:83]
	v_mfma_f32_16x16x32_bf16 v[68:71], v[170:173], v[210:213], v[68:71]
	v_mfma_f32_16x16x32_bf16 v[64:67], v[178:181], v[210:213], v[64:67]
	s_setprio 0
	s_barrier
	s_add_i32 s47, s38, s27
	v_lshl_add_u64 v[214:215], s[18:19], 0, v[130:131]
	s_mov_b32 m0, s47
	ds_read_b128 v[182:185], v153 offset:16384
	ds_read_b128 v[186:189], v153 offset:17408
	ds_read_b128 v[190:193], v153 offset:18432
	ds_read_b128 v[194:197], v153 offset:19456
	ds_read_b128 v[198:201], v153 offset:20480
	ds_read_b128 v[202:205], v153 offset:21504
	ds_read_b128 v[206:209], v153 offset:22528
	ds_read_b128 v[210:213], v153 offset:23552
	global_load_lds_dwordx4 v[214:215], off
	s_add_i32 m0, s47, 0x2000
	s_add_u32 s48, s18, 0xb0000
	v_lshl_add_u64 v[216:217], s[18:19], 0, v[134:135]
	s_addc_u32 s49, s19, 0
	s_add_i32 s47, s39, s27
	global_load_lds_dwordx4 v[216:217], off
	v_lshl_add_u64 v[218:219], s[48:49], 0, v[130:131]
	s_mov_b32 m0, s47
	v_lshl_add_u64 v[220:221], s[20:21], 0, v[132:133]
	global_load_lds_dwordx4 v[218:219], off
	v_lshl_add_u64 v[218:219], s[48:49], 0, v[134:135]
	s_add_i32 m0, s47, 0x2000
	s_nop 0
	global_load_lds_dwordx4 v[218:219], off
	v_lshl_add_u64 v[218:219], s[20:21], 0, v[128:129]
	s_mov_b32 m0, s28
	s_nop 0
	global_load_lds_dwordx4 v[218:219], off
	s_mov_b32 m0, s29
	s_nop 0
	global_load_lds_dwordx4 v[220:221], off
	s_waitcnt vmcnt(8)
	s_waitcnt lgkmcnt(0)
	s_barrier
	s_setprio 1
	s_waitcnt lgkmcnt(0)
	v_mfma_f32_16x16x32_bf16 v[60:63], v[144:147], v[182:185], v[60:63]
	v_mfma_f32_16x16x32_bf16 v[56:59], v[158:161], v[182:185], v[56:59]
	v_mfma_f32_16x16x32_bf16 v[44:47], v[144:147], v[190:193], v[44:47]
	v_mfma_f32_16x16x32_bf16 v[40:43], v[158:161], v[190:193], v[40:43]
	v_mfma_f32_16x16x32_bf16 v[28:31], v[144:147], v[198:201], v[28:31]
	v_mfma_f32_16x16x32_bf16 v[24:27], v[158:161], v[198:201], v[24:27]
	v_mfma_f32_16x16x32_bf16 v[12:15], v[144:147], v[206:209], v[12:15]
	v_mfma_f32_16x16x32_bf16 v[8:11], v[158:161], v[206:209], v[8:11]
	v_mfma_f32_16x16x32_bf16 v[60:63], v[154:157], v[186:189], v[60:63]
	v_mfma_f32_16x16x32_bf16 v[56:59], v[162:165], v[186:189], v[56:59]
	v_mfma_f32_16x16x32_bf16 v[44:47], v[154:157], v[194:197], v[44:47]
	v_mfma_f32_16x16x32_bf16 v[40:43], v[162:165], v[194:197], v[40:43]
	v_mfma_f32_16x16x32_bf16 v[28:31], v[154:157], v[202:205], v[28:31]
	v_mfma_f32_16x16x32_bf16 v[24:27], v[162:165], v[202:205], v[24:27]
	v_mfma_f32_16x16x32_bf16 v[12:15], v[154:157], v[210:213], v[12:15]
	v_mfma_f32_16x16x32_bf16 v[8:11], v[162:165], v[210:213], v[8:11]
	s_setprio 0
	s_setprio 1
	v_mfma_f32_16x16x32_bf16 v[52:55], v[166:169], v[182:185], v[52:55]
	v_mfma_f32_16x16x32_bf16 v[48:51], v[174:177], v[182:185], v[48:51]
	v_mfma_f32_16x16x32_bf16 v[36:39], v[166:169], v[190:193], v[36:39]
	v_mfma_f32_16x16x32_bf16 v[32:35], v[174:177], v[190:193], v[32:35]
	v_mfma_f32_16x16x32_bf16 v[20:23], v[166:169], v[198:201], v[20:23]
	v_mfma_f32_16x16x32_bf16 v[16:19], v[174:177], v[198:201], v[16:19]
	v_mfma_f32_16x16x32_bf16 v[4:7], v[166:169], v[206:209], v[4:7]
	v_mfma_f32_16x16x32_bf16 v[0:3], v[174:177], v[206:209], v[0:3]
	v_mfma_f32_16x16x32_bf16 v[52:55], v[170:173], v[186:189], v[52:55]
	v_mfma_f32_16x16x32_bf16 v[48:51], v[178:181], v[186:189], v[48:51]
	v_mfma_f32_16x16x32_bf16 v[36:39], v[170:173], v[194:197], v[36:39]
	v_mfma_f32_16x16x32_bf16 v[32:35], v[178:181], v[194:197], v[32:35]
	v_mfma_f32_16x16x32_bf16 v[20:23], v[170:173], v[202:205], v[20:23]
	v_mfma_f32_16x16x32_bf16 v[16:19], v[178:181], v[202:205], v[16:19]
	v_mfma_f32_16x16x32_bf16 v[4:7], v[170:173], v[210:213], v[4:7]
	v_mfma_f32_16x16x32_bf16 v[0:3], v[178:181], v[210:213], v[0:3]
	s_setprio 0
	s_barrier
; #define PG8_STAGE(bufoff, gbase, voff) do { _Pragma("unroll") for (int _i = 0; _i < 2; ++_i) \
;         __builtin_amdgcn_global_load_lds((const unsigned*)((const char*)(gbase) + (voff)[_i]), (PG8_LAS unsigned*)(lds + (bufoff) + ldsw + _i * 8192), 16, 0, 0); } while (0)
; #define PG8_LDA(dst, b, h) do { _Pragma("unroll") for (int m = 0; m < 4; ++m) _Pragma("unroll") for (int k = 0; k < 2; ++k) dst[m][k] = *(const PG8_LAS bf16x8*)(lds + PG8_SA(b, h) + aoff + m * 2048 + k * 1024); } while (0)
; #define PG8_LDB(dst, b, h) do { _Pragma("unroll") for (int n = 0; n < 2; ++n) _Pragma("unroll") for (int k = 0; k < 2; ++k) dst[n][k] = *(const PG8_LAS bf16x8*)(lds + PG8_SB(b, h) + boff + n * 2048 + k * 1024); } while (0)
; #define PG8_MMA(ai, bj, At, Bt) do { __builtin_amdgcn_s_setprio(1); _Pragma("unroll") for (int m = 0; m < 4; ++m) _Pragma("unroll") for (int n = 0; n < 2; ++n) _Pragma("unroll") for (int k = 0; k < 2; ++k) \
;         acc[ai][bj][m][n] = __builtin_amdgcn_mfma_f32_16x16x32_bf16(Bt[n][k], At[m][k], acc[ai][bj][m][n], 0, 0, 0); __builtin_amdgcn_s_setprio(0); } while (0)
; #define PG8_WAIT_V(n) asm volatile("s_waitcnt vmcnt(" #n ")" ::: "memory")
; #define PG8_WAIT_L(n) asm volatile("s_waitcnt lgkmcnt(" #n ")" ::: "memory")
; #define PG8_BAR __builtin_amdgcn_s_barrier()
; #define PG8_SCHED __builtin_amdgcn_sched_barrier(0)
; template <class Epi, class Sched, bool ALIGN_EPI = false, bool SP2 = false>
; __device__ __forceinline__ void gemm_phase(PG8_LAS unsigned char* lds, const Gemm g, const Sched& S, const Epi& E) {
;     ...
;             PG8_LDB(B0, 1, 0); PG8_LDB(B1, 1, 1); PG8_SCHED; PG8_LDA(At, 1, 0); PG8_STAGE(PG8_SA(0, 1), a2 + hstep, voffA);
;             PG8_WAIT_V(8); PG8_WAIT_L(0); PG8_BAR; PG8_MMA(0, 0, At, B0); PG8_MMA(0, 1, At, B1); PG8_BAR; PG8_SCHED;
	s_add_i32 s47, 0, 0x18000
	s_add_i32 s48, 0, 0x1c000
	v_add_u32_e32 v162, s47, v149
	v_add_u32_e32 v178, s48, v149
	ds_read_b128 v[144:147], v162
	ds_read_b128 v[154:157], v162 offset:1024
	ds_read_b128 v[158:161], v162 offset:2048
	ds_read_b128 v[162:165], v162 offset:3072
	ds_read_b128 v[166:169], v178
	ds_read_b128 v[170:173], v178 offset:1024
	ds_read_b128 v[174:177], v178 offset:2048
	ds_read_b128 v[178:181], v178 offset:3072
	s_add_u32 s20, s20, 0xb0000
	s_addc_u32 s21, s21, 0
	s_mov_b32 m0, s30
	v_lshl_add_u64 v[222:223], s[20:21], 0, v[128:129]
	ds_read_b128 v[182:185], v153 offset:32768
	ds_read_b128 v[186:189], v153 offset:33792
	ds_read_b128 v[190:193], v153 offset:34816
	ds_read_b128 v[194:197], v153 offset:35840
	ds_read_b128 v[198:201], v153 offset:36864
	ds_read_b128 v[202:205], v153 offset:37888
	ds_read_b128 v[206:209], v153 offset:38912
	ds_read_b128 v[210:213], v153 offset:39936
	global_load_lds_dwordx4 v[222:223], off
	v_lshl_add_u64 v[222:223], s[20:21], 0, v[132:133]
	s_mov_b32 m0, s31
	s_nop 0
	global_load_lds_dwordx4 v[222:223], off
	s_waitcnt vmcnt(8)
	s_waitcnt lgkmcnt(0)
	s_barrier
	s_setprio 1
	s_waitcnt lgkmcnt(0)
	v_mfma_f32_16x16x32_bf16 v[124:127], v[144:147], v[182:185], v[124:127]
	v_mfma_f32_16x16x32_bf16 v[120:123], v[158:161], v[182:185], v[120:123]
	v_mfma_f32_16x16x32_bf16 v[108:111], v[144:147], v[190:193], v[108:111]
	v_mfma_f32_16x16x32_bf16 v[104:107], v[158:161], v[190:193], v[104:107]
	v_mfma_f32_16x16x32_bf16 v[92:95], v[144:147], v[198:201], v[92:95]
	v_mfma_f32_16x16x32_bf16 v[88:91], v[158:161], v[198:201], v[88:91]
	v_mfma_f32_16x16x32_bf16 v[76:79], v[144:147], v[206:209], v[76:79]
	v_mfma_f32_16x16x32_bf16 v[72:75], v[158:161], v[206:209], v[72:75]
	v_mfma_f32_16x16x32_bf16 v[124:127], v[154:157], v[186:189], v[124:127]
	v_mfma_f32_16x16x32_bf16 v[120:123], v[162:165], v[186:189], v[120:123]
	v_mfma_f32_16x16x32_bf16 v[108:111], v[154:157], v[194:197], v[108:111]
	v_mfma_f32_16x16x32_bf16 v[104:107], v[162:165], v[194:197], v[104:107]
	v_mfma_f32_16x16x32_bf16 v[92:95], v[154:157], v[202:205], v[92:95]
	v_mfma_f32_16x16x32_bf16 v[88:91], v[162:165], v[202:205], v[88:91]
	v_mfma_f32_16x16x32_bf16 v[76:79], v[154:157], v[210:213], v[76:79]
	v_mfma_f32_16x16x32_bf16 v[72:75], v[162:165], v[210:213], v[72:75]
	s_setprio 0
	s_setprio 1
	v_mfma_f32_16x16x32_bf16 v[116:119], v[166:169], v[182:185], v[116:119]
	v_mfma_f32_16x16x32_bf16 v[112:115], v[174:177], v[182:185], v[112:115]
	v_mfma_f32_16x16x32_bf16 v[100:103], v[166:169], v[190:193], v[100:103]
	v_mfma_f32_16x16x32_bf16 v[96:99], v[174:177], v[190:193], v[96:99]
	v_mfma_f32_16x16x32_bf16 v[84:87], v[166:169], v[198:201], v[84:87]
	v_mfma_f32_16x16x32_bf16 v[80:83], v[174:177], v[198:201], v[80:83]
	v_mfma_f32_16x16x32_bf16 v[68:71], v[166:169], v[206:209], v[68:71]
	v_mfma_f32_16x16x32_bf16 v[64:67], v[174:177], v[206:209], v[64:67]
	v_mfma_f32_16x16x32_bf16 v[116:119], v[170:173], v[186:189], v[116:119]
	v_mfma_f32_16x16x32_bf16 v[112:115], v[178:181], v[186:189], v[112:115]
	v_mfma_f32_16x16x32_bf16 v[100:103], v[170:173], v[194:197], v[100:103]
	v_mfma_f32_16x16x32_bf16 v[96:99], v[178:181], v[194:197], v[96:99]
	v_mfma_f32_16x16x32_bf16 v[84:87], v[170:173], v[202:205], v[84:87]
	v_mfma_f32_16x16x32_bf16 v[80:83], v[178:181], v[202:205], v[80:83]
	v_mfma_f32_16x16x32_bf16 v[68:71], v[170:173], v[210:213], v[68:71]
	v_mfma_f32_16x16x32_bf16 v[64:67], v[178:181], v[210:213], v[64:67]
	s_setprio 0
	s_barrier
; #define PG8_STAGE(bufoff, gbase, voff) do { _Pragma("unroll") for (int _i = 0; _i < 2; ++_i) \
;         __builtin_amdgcn_global_load_lds((const unsigned*)((const char*)(gbase) + (voff)[_i]), (PG8_LAS unsigned*)(lds + (bufoff) + ldsw + _i * 8192), 16, 0, 0); } while (0)
; #define PG8_LDA(dst, b, h) do { _Pragma("unroll") for (int m = 0; m < 4; ++m) _Pragma("unroll") for (int k = 0; k < 2; ++k) dst[m][k] = *(const PG8_LAS bf16x8*)(lds + PG8_SA(b, h) + aoff + m * 2048 + k * 1024); } while (0)
; #define PG8_MMA(ai, bj, At, Bt) do { __builtin_amdgcn_s_setprio(1); _Pragma("unroll") for (int m = 0; m < 4; ++m) _Pragma("unroll") for (int n = 0; n < 2; ++n) _Pragma("unroll") for (int k = 0; k < 2; ++k) \
;         acc[ai][bj][m][n] = __builtin_amdgcn_mfma_f32_16x16x32_bf16(Bt[n][k], At[m][k], acc[ai][bj][m][n], 0, 0, 0); __builtin_amdgcn_s_setprio(0); } while (0)
; #define PG8_WAIT_V(n) asm volatile("s_waitcnt vmcnt(" #n ")" ::: "memory")
; #define PG8_WAIT_L(n) asm volatile("s_waitcnt lgkmcnt(" #n ")" ::: "memory")
; #define PG8_BAR __builtin_amdgcn_s_barrier()
; #define PG8_SCHED __builtin_amdgcn_sched_barrier(0)
; template <class Epi, class Sched, bool ALIGN_EPI = false, bool SP2 = false>
; __device__ __forceinline__ void gemm_phase(PG8_LAS unsigned char* lds, const Gemm g, const Sched& S, const Epi& E) {
;     ...
;         for (int t = 0; t < nt; t += 2) {
;             const bool last = (t == nt - 2);
;             const char* a1 = cA + (size_t)(t + 1) * kstep;
;             const char* a2 = last ? nA : cA + (size_t)(t + 2) * kstep; const char* b2 = last ? nB : cB + (size_t)(t + 2) * kstep;
;             const char* a3 = a2 + kstep; const char* b3 = b2 + kstep;
;     ...
;             PG8_LDA(At, 1, 1); PG8_STAGE(PG8_SB(1, 0), b3, voffB); PG8_STAGE(PG8_SB(1, 1), b3 + hstep, voffB); PG8_STAGE(PG8_SA(1, 0), a3, voffA);
;             PG8_WAIT_V(8); PG8_WAIT_L(0); PG8_BAR; PG8_MMA(1, 0, At, B0); PG8_MMA(1, 1, At, B1); PG8_BAR; PG8_SCHED;
	s_add_i32 s20, s47, s27
	v_lshl_add_u64 v[214:215], v[214:215], 0, s[8:9]
	s_mov_b32 m0, s20
	ds_read_b128 v[182:185], v153 offset:49152
	ds_read_b128 v[186:189], v153 offset:50176
	ds_read_b128 v[190:193], v153 offset:51200
	ds_read_b128 v[194:197], v153 offset:52224
	ds_read_b128 v[198:201], v153 offset:53248
	ds_read_b128 v[202:205], v153 offset:54272
	ds_read_b128 v[206:209], v153 offset:55296
	ds_read_b128 v[210:213], v153 offset:56320
	global_load_lds_dwordx4 v[214:215], off
	s_add_i32 m0, s20, 0x2000
	s_add_u32 s18, s18, 0xb0080
	v_lshl_add_u64 v[214:215], v[216:217], 0, s[8:9]
	s_addc_u32 s19, s19, 0
	s_add_i32 s20, s48, s27
	global_load_lds_dwordx4 v[214:215], off
	v_lshl_add_u64 v[214:215], s[18:19], 0, v[130:131]
	s_mov_b32 m0, s20
	s_nop 0
	global_load_lds_dwordx4 v[214:215], off
	v_lshl_add_u64 v[214:215], s[18:19], 0, v[134:135]
	s_add_i32 m0, s20, 0x2000
	s_nop 0
	global_load_lds_dwordx4 v[214:215], off
	v_lshl_add_u64 v[214:215], v[218:219], 0, s[8:9]
	s_mov_b32 m0, s35
	s_nop 0
	global_load_lds_dwordx4 v[214:215], off
	v_lshl_add_u64 v[214:215], v[220:221], 0, s[8:9]
	s_mov_b32 m0, s36
	s_nop 0
	global_load_lds_dwordx4 v[214:215], off
	s_waitcnt vmcnt(8)
	s_waitcnt lgkmcnt(0)
	s_barrier
	s_setprio 1
	s_waitcnt lgkmcnt(0)
	v_mfma_f32_16x16x32_bf16 v[60:63], v[144:147], v[182:185], v[60:63]
	v_mfma_f32_16x16x32_bf16 v[56:59], v[158:161], v[182:185], v[56:59]
	v_mfma_f32_16x16x32_bf16 v[44:47], v[144:147], v[190:193], v[44:47]
	v_mfma_f32_16x16x32_bf16 v[40:43], v[158:161], v[190:193], v[40:43]
	v_mfma_f32_16x16x32_bf16 v[28:31], v[144:147], v[198:201], v[28:31]
	v_mfma_f32_16x16x32_bf16 v[24:27], v[158:161], v[198:201], v[24:27]
	v_mfma_f32_16x16x32_bf16 v[12:15], v[144:147], v[206:209], v[12:15]
	v_mfma_f32_16x16x32_bf16 v[8:11], v[158:161], v[206:209], v[8:11]
	v_mfma_f32_16x16x32_bf16 v[60:63], v[154:157], v[186:189], v[60:63]
	v_mfma_f32_16x16x32_bf16 v[56:59], v[162:165], v[186:189], v[56:59]
	v_mfma_f32_16x16x32_bf16 v[44:47], v[154:157], v[194:197], v[44:47]
	v_mfma_f32_16x16x32_bf16 v[40:43], v[162:165], v[194:197], v[40:43]
	v_mfma_f32_16x16x32_bf16 v[28:31], v[154:157], v[202:205], v[28:31]
	v_mfma_f32_16x16x32_bf16 v[24:27], v[162:165], v[202:205], v[24:27]
	v_mfma_f32_16x16x32_bf16 v[12:15], v[154:157], v[210:213], v[12:15]
	v_mfma_f32_16x16x32_bf16 v[8:11], v[162:165], v[210:213], v[8:11]
	s_setprio 0
	s_setprio 1
	v_mfma_f32_16x16x32_bf16 v[52:55], v[166:169], v[182:185], v[52:55]
	v_mfma_f32_16x16x32_bf16 v[48:51], v[174:177], v[182:185], v[48:51]
	v_mfma_f32_16x16x32_bf16 v[36:39], v[166:169], v[190:193], v[36:39]
	v_mfma_f32_16x16x32_bf16 v[32:35], v[174:177], v[190:193], v[32:35]
	v_mfma_f32_16x16x32_bf16 v[20:23], v[166:169], v[198:201], v[20:23]
	v_mfma_f32_16x16x32_bf16 v[16:19], v[174:177], v[198:201], v[16:19]
	v_mfma_f32_16x16x32_bf16 v[4:7], v[166:169], v[206:209], v[4:7]
	v_mfma_f32_16x16x32_bf16 v[0:3], v[174:177], v[206:209], v[0:3]
	v_mfma_f32_16x16x32_bf16 v[52:55], v[170:173], v[186:189], v[52:55]
	v_mfma_f32_16x16x32_bf16 v[48:51], v[178:181], v[186:189], v[48:51]
	v_mfma_f32_16x16x32_bf16 v[36:39], v[170:173], v[194:197], v[36:39]
	v_mfma_f32_16x16x32_bf16 v[32:35], v[178:181], v[194:197], v[32:35]
	v_mfma_f32_16x16x32_bf16 v[20:23], v[170:173], v[202:205], v[20:23]
	v_mfma_f32_16x16x32_bf16 v[16:19], v[178:181], v[202:205], v[16:19]
	v_mfma_f32_16x16x32_bf16 v[4:7], v[170:173], v[210:213], v[4:7]
	v_mfma_f32_16x16x32_bf16 v[0:3], v[178:181], v[210:213], v[0:3]
	s_setprio 0
	s_add_i32 s46, s46, 2
	s_add_u32 s16, s16, 0x100
	s_addc_u32 s17, s17, 0
	s_add_u32 s44, s44, 0x100
	s_addc_u32 s45, s45, 0
	s_cmp_gt_u32 s46, 41
	s_barrier
	s_cbranch_scc0 .LBB0_1190
	s_and_b64 vcc, exec, s[10:11]
	s_cbranch_vccz .LBB0_1193
	s_barrier
